# attention softmax under PV MFMAs + GEMM loop trims (redundant setprio pairs, merged waits, nop after m0 write filled by address add)
# speedup vs baseline: 1.0039x; 1.0039x over previous
.LBB0_282:
	s_add_i32 s44, s38, 2
	s_add_u32 s36, s6, 0xfff80080
	s_addc_u32 s37, s7, -1
	s_add_i32 s45, 0, 0x10000
	s_cmp_eq_u32 s41, s38
	s_cselect_b32 s39, s59, s37
	s_cselect_b32 s38, s58, s36
	v_add_u32_e32 v96, s45, v141
	s_cselect_b32 s37, s65, s43
	s_cselect_b32 s36, s64, s42
	s_add_i32 s50, 0, 0x14000
	ds_read_b128 v[150:153], v96
	ds_read_b128 v[154:157], v96 offset:1024
	ds_read_b128 v[158:161], v96 offset:2048
	ds_read_b128 v[162:165], v96 offset:3072
	v_add_u32_e32 v96, s50, v141
	ds_read_b128 v[166:169], v96
	ds_read_b128 v[170:173], v96 offset:1024
	ds_read_b128 v[174:177], v96 offset:2048
	ds_read_b128 v[178:181], v96 offset:3072
	v_lshl_add_u64 v[196:197], s[6:7], 0, v[146:147]
	s_add_i32 m0, s1, 0xc000
	ds_read_b128 v[182:185], v139
	ds_read_b128 v[186:189], v139 offset:1024
	ds_read_b128 v[190:193], v139 offset:2048
	ds_read_b128 v[204:207], v139 offset:3072
	ds_read_b128 v[208:211], v139 offset:4096
	ds_read_b128 v[212:215], v139 offset:5120
	ds_read_b128 v[216:219], v139 offset:6144
	ds_read_b128 v[220:223], v139 offset:7168
	global_load_lds_dwordx4 v[196:197], off
	s_add_i32 m0, s1, 0xe000
	v_lshl_add_u64 v[196:197], s[6:7], 0, v[148:149]
	global_load_lds_dwordx4 v[196:197], off
	s_waitcnt vmcnt(8) lgkmcnt(0)
	s_barrier
	s_setprio 1
	v_mfma_f32_16x16x32_bf16 v[126:129], v[150:153], v[182:185], v[126:129]
	v_mfma_f32_16x16x32_bf16 v[122:125], v[158:161], v[182:185], v[122:125]
	v_mfma_f32_16x16x32_bf16 v[118:121], v[150:153], v[190:193], v[118:121]
	v_mfma_f32_16x16x32_bf16 v[110:113], v[158:161], v[190:193], v[110:113]
	v_mfma_f32_16x16x32_bf16 v[102:105], v[150:153], v[208:211], v[102:105]
	v_mfma_f32_16x16x32_bf16 v[92:95], v[158:161], v[208:211], v[92:95]
	v_mfma_f32_16x16x32_bf16 v[84:87], v[150:153], v[216:219], v[84:87]
	v_mfma_f32_16x16x32_bf16 v[76:79], v[158:161], v[216:219], v[76:79]
	v_mfma_f32_16x16x32_bf16 v[126:129], v[154:157], v[186:189], v[126:129]
	v_mfma_f32_16x16x32_bf16 v[122:125], v[162:165], v[186:189], v[122:125]
	v_mfma_f32_16x16x32_bf16 v[118:121], v[154:157], v[204:207], v[118:121]
	v_mfma_f32_16x16x32_bf16 v[110:113], v[162:165], v[204:207], v[110:113]
	v_mfma_f32_16x16x32_bf16 v[102:105], v[154:157], v[212:215], v[102:105]
	v_mfma_f32_16x16x32_bf16 v[92:95], v[162:165], v[212:215], v[92:95]
	v_mfma_f32_16x16x32_bf16 v[84:87], v[154:157], v[220:223], v[84:87]
	v_mfma_f32_16x16x32_bf16 v[76:79], v[162:165], v[220:223], v[76:79]
	v_mfma_f32_16x16x32_bf16 v[114:117], v[166:169], v[182:185], v[114:117]
	v_mfma_f32_16x16x32_bf16 v[106:109], v[174:177], v[182:185], v[106:109]
	v_mfma_f32_16x16x32_bf16 v[98:101], v[166:169], v[190:193], v[98:101]
	v_mfma_f32_16x16x32_bf16 v[88:91], v[174:177], v[190:193], v[88:91]
	v_mfma_f32_16x16x32_bf16 v[80:83], v[166:169], v[208:211], v[80:83]
	v_mfma_f32_16x16x32_bf16 v[72:75], v[174:177], v[208:211], v[72:75]
	v_mfma_f32_16x16x32_bf16 v[68:71], v[166:169], v[216:219], v[68:71]
	v_mfma_f32_16x16x32_bf16 v[64:67], v[174:177], v[216:219], v[64:67]
	v_mfma_f32_16x16x32_bf16 v[114:117], v[170:173], v[186:189], v[114:117]
	v_mfma_f32_16x16x32_bf16 v[106:109], v[178:181], v[186:189], v[106:109]
	v_mfma_f32_16x16x32_bf16 v[98:101], v[170:173], v[204:207], v[98:101]
	v_mfma_f32_16x16x32_bf16 v[88:91], v[178:181], v[204:207], v[88:91]
	v_mfma_f32_16x16x32_bf16 v[80:83], v[170:173], v[212:215], v[80:83]
	v_mfma_f32_16x16x32_bf16 v[72:75], v[178:181], v[212:215], v[72:75]
	v_mfma_f32_16x16x32_bf16 v[68:71], v[170:173], v[220:223], v[68:71]
	v_mfma_f32_16x16x32_bf16 v[64:67], v[178:181], v[220:223], v[64:67]
	s_setprio 0
	s_barrier
	s_add_i32 s45, s45, s0
	v_lshl_add_u64 v[196:197], s[36:37], 0, v[132:133]
	s_mov_b32 m0, s45
	ds_read_b128 v[182:185], v139 offset:16384
	ds_read_b128 v[186:189], v139 offset:17408
	ds_read_b128 v[190:193], v139 offset:18432
	ds_read_b128 v[204:207], v139 offset:19456
	ds_read_b128 v[208:211], v139 offset:20480
	ds_read_b128 v[212:215], v139 offset:21504
	ds_read_b128 v[216:219], v139 offset:22528
	ds_read_b128 v[220:223], v139 offset:23552
	global_load_lds_dwordx4 v[196:197], off
	s_add_i32 m0, s45, 0x2000
	s_add_u32 s46, s36, 0x80000
	v_lshl_add_u64 v[198:199], s[36:37], 0, v[136:137]
	s_addc_u32 s47, s37, 0
	s_add_i32 s45, s50, s0
	global_load_lds_dwordx4 v[198:199], off
	v_lshl_add_u64 v[200:201], s[46:47], 0, v[132:133]
	s_mov_b32 m0, s45
	v_lshl_add_u64 v[202:203], s[38:39], 0, v[134:135]
	global_load_lds_dwordx4 v[200:201], off
	s_add_i32 m0, s45, 0x2000
	v_lshl_add_u64 v[200:201], s[46:47], 0, v[136:137]
	global_load_lds_dwordx4 v[200:201], off
	s_mov_b32 m0, s1
	v_lshl_add_u64 v[200:201], s[38:39], 0, v[130:131]
	global_load_lds_dwordx4 v[200:201], off
	s_mov_b32 m0, s15
	s_nop 0
	global_load_lds_dwordx4 v[202:203], off
	s_waitcnt vmcnt(8) lgkmcnt(0)
	s_barrier
	s_setprio 1
	v_mfma_f32_16x16x32_bf16 v[60:63], v[150:153], v[182:185], v[60:63]
	v_mfma_f32_16x16x32_bf16 v[56:59], v[158:161], v[182:185], v[56:59]
	v_mfma_f32_16x16x32_bf16 v[52:55], v[150:153], v[190:193], v[52:55]
	v_mfma_f32_16x16x32_bf16 v[44:47], v[158:161], v[190:193], v[44:47]
	v_mfma_f32_16x16x32_bf16 v[36:39], v[150:153], v[208:211], v[36:39]
	v_mfma_f32_16x16x32_bf16 v[28:31], v[158:161], v[208:211], v[28:31]
	v_mfma_f32_16x16x32_bf16 v[20:23], v[150:153], v[216:219], v[20:23]
	v_mfma_f32_16x16x32_bf16 v[12:15], v[158:161], v[216:219], v[12:15]
	v_mfma_f32_16x16x32_bf16 v[60:63], v[154:157], v[186:189], v[60:63]
	v_mfma_f32_16x16x32_bf16 v[56:59], v[162:165], v[186:189], v[56:59]
	v_mfma_f32_16x16x32_bf16 v[52:55], v[154:157], v[204:207], v[52:55]
	v_mfma_f32_16x16x32_bf16 v[44:47], v[162:165], v[204:207], v[44:47]
	v_mfma_f32_16x16x32_bf16 v[36:39], v[154:157], v[212:215], v[36:39]
	v_mfma_f32_16x16x32_bf16 v[28:31], v[162:165], v[212:215], v[28:31]
	v_mfma_f32_16x16x32_bf16 v[20:23], v[154:157], v[220:223], v[20:23]
	v_mfma_f32_16x16x32_bf16 v[12:15], v[162:165], v[220:223], v[12:15]
	v_mfma_f32_16x16x32_bf16 v[48:51], v[166:169], v[182:185], v[48:51]
	v_mfma_f32_16x16x32_bf16 v[40:43], v[174:177], v[182:185], v[40:43]
	v_mfma_f32_16x16x32_bf16 v[32:35], v[166:169], v[190:193], v[32:35]
	v_mfma_f32_16x16x32_bf16 v[24:27], v[174:177], v[190:193], v[24:27]
	v_mfma_f32_16x16x32_bf16 v[16:19], v[166:169], v[208:211], v[16:19]
	v_mfma_f32_16x16x32_bf16 v[8:11], v[174:177], v[208:211], v[8:11]
	v_mfma_f32_16x16x32_bf16 v[4:7], v[166:169], v[216:219], v[4:7]
	v_mfma_f32_16x16x32_bf16 v[0:3], v[174:177], v[216:219], v[0:3]
	v_mfma_f32_16x16x32_bf16 v[48:51], v[170:173], v[186:189], v[48:51]
	v_mfma_f32_16x16x32_bf16 v[40:43], v[178:181], v[186:189], v[40:43]
	v_mfma_f32_16x16x32_bf16 v[32:35], v[170:173], v[204:207], v[32:35]
	v_mfma_f32_16x16x32_bf16 v[24:27], v[178:181], v[204:207], v[24:27]
	v_mfma_f32_16x16x32_bf16 v[16:19], v[170:173], v[212:215], v[16:19]
	v_mfma_f32_16x16x32_bf16 v[8:11], v[178:181], v[212:215], v[8:11]
	v_mfma_f32_16x16x32_bf16 v[4:7], v[170:173], v[220:223], v[4:7]
	v_mfma_f32_16x16x32_bf16 v[0:3], v[178:181], v[220:223], v[0:3]
	s_setprio 0
	s_barrier
	s_add_i32 s45, 0, 0x18000
	v_add_u32_e32 v96, s45, v141
	s_add_i32 s46, 0, 0x1c000
	ds_read_b128 v[150:153], v96
	ds_read_b128 v[154:157], v96 offset:1024
	ds_read_b128 v[158:161], v96 offset:2048
	ds_read_b128 v[162:165], v96 offset:3072
	v_add_u32_e32 v96, s46, v141
	ds_read_b128 v[166:169], v96
	ds_read_b128 v[170:173], v96 offset:1024
	ds_read_b128 v[174:177], v96 offset:2048
	ds_read_b128 v[178:181], v96 offset:3072
	s_add_u32 s38, s38, 0x80000
	s_addc_u32 s39, s39, 0
	s_mov_b32 m0, s23
	v_lshl_add_u64 v[224:225], s[38:39], 0, v[130:131]
	ds_read_b128 v[182:185], v139 offset:32768
	ds_read_b128 v[186:189], v139 offset:33792
	ds_read_b128 v[190:193], v139 offset:34816
	ds_read_b128 v[204:207], v139 offset:35840
	ds_read_b128 v[208:211], v139 offset:36864
	ds_read_b128 v[212:215], v139 offset:37888
	ds_read_b128 v[216:219], v139 offset:38912
	ds_read_b128 v[220:223], v139 offset:39936
	global_load_lds_dwordx4 v[224:225], off
	s_mov_b32 m0, s48
	v_lshl_add_u64 v[224:225], s[38:39], 0, v[134:135]
	global_load_lds_dwordx4 v[224:225], off
	s_waitcnt vmcnt(8) lgkmcnt(0)
	s_barrier
	s_setprio 1
	v_mfma_f32_16x16x32_bf16 v[126:129], v[150:153], v[182:185], v[126:129]
	v_mfma_f32_16x16x32_bf16 v[122:125], v[158:161], v[182:185], v[122:125]
	v_mfma_f32_16x16x32_bf16 v[118:121], v[150:153], v[190:193], v[118:121]
	v_mfma_f32_16x16x32_bf16 v[110:113], v[158:161], v[190:193], v[110:113]
	v_mfma_f32_16x16x32_bf16 v[102:105], v[150:153], v[208:211], v[102:105]
	v_mfma_f32_16x16x32_bf16 v[92:95], v[158:161], v[208:211], v[92:95]
	v_mfma_f32_16x16x32_bf16 v[84:87], v[150:153], v[216:219], v[84:87]
	v_mfma_f32_16x16x32_bf16 v[76:79], v[158:161], v[216:219], v[76:79]
	v_mfma_f32_16x16x32_bf16 v[126:129], v[154:157], v[186:189], v[126:129]
	v_mfma_f32_16x16x32_bf16 v[122:125], v[162:165], v[186:189], v[122:125]
	v_mfma_f32_16x16x32_bf16 v[118:121], v[154:157], v[204:207], v[118:121]
	v_mfma_f32_16x16x32_bf16 v[110:113], v[162:165], v[204:207], v[110:113]
	v_mfma_f32_16x16x32_bf16 v[102:105], v[154:157], v[212:215], v[102:105]
	v_mfma_f32_16x16x32_bf16 v[92:95], v[162:165], v[212:215], v[92:95]
	v_mfma_f32_16x16x32_bf16 v[84:87], v[154:157], v[220:223], v[84:87]
	v_mfma_f32_16x16x32_bf16 v[76:79], v[162:165], v[220:223], v[76:79]
	v_mfma_f32_16x16x32_bf16 v[114:117], v[166:169], v[182:185], v[114:117]
	v_mfma_f32_16x16x32_bf16 v[106:109], v[174:177], v[182:185], v[106:109]
	v_mfma_f32_16x16x32_bf16 v[98:101], v[166:169], v[190:193], v[98:101]
	v_mfma_f32_16x16x32_bf16 v[88:91], v[174:177], v[190:193], v[88:91]
	v_mfma_f32_16x16x32_bf16 v[80:83], v[166:169], v[208:211], v[80:83]
	v_mfma_f32_16x16x32_bf16 v[72:75], v[174:177], v[208:211], v[72:75]
	v_mfma_f32_16x16x32_bf16 v[68:71], v[166:169], v[216:219], v[68:71]
	v_mfma_f32_16x16x32_bf16 v[64:67], v[174:177], v[216:219], v[64:67]
	v_mfma_f32_16x16x32_bf16 v[114:117], v[170:173], v[186:189], v[114:117]
	v_mfma_f32_16x16x32_bf16 v[106:109], v[178:181], v[186:189], v[106:109]
	v_mfma_f32_16x16x32_bf16 v[98:101], v[170:173], v[204:207], v[98:101]
	v_mfma_f32_16x16x32_bf16 v[88:91], v[178:181], v[204:207], v[88:91]
	v_mfma_f32_16x16x32_bf16 v[80:83], v[170:173], v[212:215], v[80:83]
	v_mfma_f32_16x16x32_bf16 v[72:75], v[178:181], v[212:215], v[72:75]
	v_mfma_f32_16x16x32_bf16 v[68:71], v[170:173], v[220:223], v[68:71]
	v_mfma_f32_16x16x32_bf16 v[64:67], v[178:181], v[220:223], v[64:67]
	s_setprio 0
	s_barrier
	s_add_i32 s38, s45, s0
	v_lshl_add_u64 v[196:197], v[196:197], 0, s[82:83]
	s_mov_b32 m0, s38
	ds_read_b128 v[182:185], v139 offset:49152
	ds_read_b128 v[186:189], v139 offset:50176
	ds_read_b128 v[190:193], v139 offset:51200
	ds_read_b128 v[204:207], v139 offset:52224
	ds_read_b128 v[208:211], v139 offset:53248
	ds_read_b128 v[212:215], v139 offset:54272
	ds_read_b128 v[216:219], v139 offset:55296
	ds_read_b128 v[220:223], v139 offset:56320
	global_load_lds_dwordx4 v[196:197], off
	s_add_i32 m0, s38, 0x2000
	s_add_u32 s36, s36, 0x80080
	v_lshl_add_u64 v[196:197], v[198:199], 0, s[82:83]
	s_addc_u32 s37, s37, 0
	s_add_i32 s38, s46, s0
	global_load_lds_dwordx4 v[196:197], off
	s_mov_b32 m0, s38
	v_lshl_add_u64 v[196:197], s[36:37], 0, v[132:133]
	global_load_lds_dwordx4 v[196:197], off
	s_add_i32 m0, s38, 0x2000
	v_lshl_add_u64 v[196:197], s[36:37], 0, v[136:137]
	global_load_lds_dwordx4 v[196:197], off
	s_mov_b32 m0, s49
	v_lshl_add_u64 v[196:197], v[200:201], 0, s[82:83]
	global_load_lds_dwordx4 v[196:197], off
	s_mov_b32 m0, s61
	v_lshl_add_u64 v[196:197], v[202:203], 0, s[82:83]
	global_load_lds_dwordx4 v[196:197], off
	s_waitcnt vmcnt(8) lgkmcnt(0)
	s_barrier
	s_setprio 1
	v_mfma_f32_16x16x32_bf16 v[60:63], v[150:153], v[182:185], v[60:63]
	v_mfma_f32_16x16x32_bf16 v[56:59], v[158:161], v[182:185], v[56:59]
	v_mfma_f32_16x16x32_bf16 v[52:55], v[150:153], v[190:193], v[52:55]
	v_mfma_f32_16x16x32_bf16 v[44:47], v[158:161], v[190:193], v[44:47]
	v_mfma_f32_16x16x32_bf16 v[36:39], v[150:153], v[208:211], v[36:39]
	v_mfma_f32_16x16x32_bf16 v[28:31], v[158:161], v[208:211], v[28:31]
	v_mfma_f32_16x16x32_bf16 v[20:23], v[150:153], v[216:219], v[20:23]
	v_mfma_f32_16x16x32_bf16 v[12:15], v[158:161], v[216:219], v[12:15]
	v_mfma_f32_16x16x32_bf16 v[60:63], v[154:157], v[186:189], v[60:63]
	v_mfma_f32_16x16x32_bf16 v[56:59], v[162:165], v[186:189], v[56:59]
	v_mfma_f32_16x16x32_bf16 v[52:55], v[154:157], v[204:207], v[52:55]
	v_mfma_f32_16x16x32_bf16 v[44:47], v[162:165], v[204:207], v[44:47]
	v_mfma_f32_16x16x32_bf16 v[36:39], v[154:157], v[212:215], v[36:39]
	v_mfma_f32_16x16x32_bf16 v[28:31], v[162:165], v[212:215], v[28:31]
	v_mfma_f32_16x16x32_bf16 v[20:23], v[154:157], v[220:223], v[20:23]
	v_mfma_f32_16x16x32_bf16 v[12:15], v[162:165], v[220:223], v[12:15]
	v_mfma_f32_16x16x32_bf16 v[48:51], v[166:169], v[182:185], v[48:51]
	v_mfma_f32_16x16x32_bf16 v[40:43], v[174:177], v[182:185], v[40:43]
	v_mfma_f32_16x16x32_bf16 v[32:35], v[166:169], v[190:193], v[32:35]
	v_mfma_f32_16x16x32_bf16 v[24:27], v[174:177], v[190:193], v[24:27]
	v_mfma_f32_16x16x32_bf16 v[16:19], v[166:169], v[208:211], v[16:19]
	v_mfma_f32_16x16x32_bf16 v[8:11], v[174:177], v[208:211], v[8:11]
	v_mfma_f32_16x16x32_bf16 v[4:7], v[166:169], v[216:219], v[4:7]
	v_mfma_f32_16x16x32_bf16 v[0:3], v[174:177], v[216:219], v[0:3]
	v_mfma_f32_16x16x32_bf16 v[48:51], v[170:173], v[186:189], v[48:51]
	v_mfma_f32_16x16x32_bf16 v[40:43], v[178:181], v[186:189], v[40:43]
	v_mfma_f32_16x16x32_bf16 v[32:35], v[170:173], v[204:207], v[32:35]
	v_mfma_f32_16x16x32_bf16 v[24:27], v[178:181], v[204:207], v[24:27]
	v_mfma_f32_16x16x32_bf16 v[16:19], v[170:173], v[212:215], v[16:19]
	v_mfma_f32_16x16x32_bf16 v[8:11], v[178:181], v[212:215], v[8:11]
	v_mfma_f32_16x16x32_bf16 v[4:7], v[170:173], v[220:223], v[4:7]
	v_mfma_f32_16x16x32_bf16 v[0:3], v[178:181], v[220:223], v[0:3]
	s_setprio 0
	s_barrier
	s_add_u32 s6, s6, 0x100
	s_addc_u32 s7, s7, 0
	s_add_u32 s42, s42, 0x100
	s_addc_u32 s43, s43, 0
	s_cmp_ge_i32 s44, s40
	s_mov_b32 s38, s44
	s_cbranch_scc0 .LBB0_282
	s_and_b64 vcc, exec, s[16:17]
	s_cbranch_vccz .LBB0_287
	s_barrier
	s_cmp_lg_u32 s55, 1
	s_mov_b64 s[6:7], -1
	s_cbranch_scc1 .LBB0_288

.LBB0_437:
	s_add_u32 s22, s20, 0xfffe0080
	s_addc_u32 s23, s21, -1
	s_add_i32 s46, 0, 0x10000
	s_cmp_eq_u32 s54, 4
	s_cselect_b32 s37, s15, s23
	s_cselect_b32 s36, s14, s22
	v_add_u32_e32 v142, s46, v145
	s_cselect_b32 s23, s17, s19
	s_cselect_b32 s22, s16, s13
	s_add_i32 s50, 0, 0x14000
	ds_read_b128 v[148:151], v142
	ds_read_b128 v[152:155], v142 offset:1024
	ds_read_b128 v[156:159], v142 offset:2048
	ds_read_b128 v[160:163], v142 offset:3072
	v_add_u32_e32 v142, s50, v145
	ds_read_b128 v[164:167], v142
	ds_read_b128 v[168:171], v142 offset:1024
	ds_read_b128 v[172:175], v142 offset:2048
	ds_read_b128 v[176:179], v142 offset:3072
	v_lshl_add_u64 v[142:143], s[20:21], 0, v[138:139]
	s_add_i32 m0, s38, 0xc000
	ds_read_b128 v[180:183], v146
	ds_read_b128 v[184:187], v146 offset:1024
	ds_read_b128 v[188:191], v146 offset:2048
	ds_read_b128 v[204:207], v146 offset:3072
	ds_read_b128 v[208:211], v146 offset:4096
	ds_read_b128 v[212:215], v146 offset:5120
	ds_read_b128 v[216:219], v146 offset:6144
	ds_read_b128 v[220:223], v146 offset:7168
	global_load_lds_dwordx4 v[142:143], off
	s_add_i32 m0, s38, 0xe000
	v_lshl_add_u64 v[142:143], s[20:21], 0, v[140:141]
	global_load_lds_dwordx4 v[142:143], off
	s_waitcnt vmcnt(8) lgkmcnt(0)
	s_barrier
	s_setprio 1
	v_mfma_f32_16x16x32_bf16 v[126:129], v[148:151], v[180:183], v[126:129]
	v_mfma_f32_16x16x32_bf16 v[122:125], v[156:159], v[180:183], v[122:125]
	v_mfma_f32_16x16x32_bf16 v[118:121], v[148:151], v[188:191], v[118:121]
	v_mfma_f32_16x16x32_bf16 v[110:113], v[156:159], v[188:191], v[110:113]
	v_mfma_f32_16x16x32_bf16 v[102:105], v[148:151], v[208:211], v[102:105]
	v_mfma_f32_16x16x32_bf16 v[92:95], v[156:159], v[208:211], v[92:95]
	v_mfma_f32_16x16x32_bf16 v[84:87], v[148:151], v[216:219], v[84:87]
	v_mfma_f32_16x16x32_bf16 v[76:79], v[156:159], v[216:219], v[76:79]
	v_mfma_f32_16x16x32_bf16 v[126:129], v[152:155], v[184:187], v[126:129]
	v_mfma_f32_16x16x32_bf16 v[122:125], v[160:163], v[184:187], v[122:125]
	v_mfma_f32_16x16x32_bf16 v[118:121], v[152:155], v[204:207], v[118:121]
	v_mfma_f32_16x16x32_bf16 v[110:113], v[160:163], v[204:207], v[110:113]
	v_mfma_f32_16x16x32_bf16 v[102:105], v[152:155], v[212:215], v[102:105]
	v_mfma_f32_16x16x32_bf16 v[92:95], v[160:163], v[212:215], v[92:95]
	v_mfma_f32_16x16x32_bf16 v[84:87], v[152:155], v[220:223], v[84:87]
	v_mfma_f32_16x16x32_bf16 v[76:79], v[160:163], v[220:223], v[76:79]
	v_mfma_f32_16x16x32_bf16 v[114:117], v[164:167], v[180:183], v[114:117]
	v_mfma_f32_16x16x32_bf16 v[106:109], v[172:175], v[180:183], v[106:109]
	v_mfma_f32_16x16x32_bf16 v[98:101], v[164:167], v[188:191], v[98:101]
	v_mfma_f32_16x16x32_bf16 v[88:91], v[172:175], v[188:191], v[88:91]
	v_mfma_f32_16x16x32_bf16 v[80:83], v[164:167], v[208:211], v[80:83]
	v_mfma_f32_16x16x32_bf16 v[72:75], v[172:175], v[208:211], v[72:75]
	v_mfma_f32_16x16x32_bf16 v[68:71], v[164:167], v[216:219], v[68:71]
	v_mfma_f32_16x16x32_bf16 v[64:67], v[172:175], v[216:219], v[64:67]
	v_mfma_f32_16x16x32_bf16 v[114:117], v[168:171], v[184:187], v[114:117]
	v_mfma_f32_16x16x32_bf16 v[106:109], v[176:179], v[184:187], v[106:109]
	v_mfma_f32_16x16x32_bf16 v[98:101], v[168:171], v[204:207], v[98:101]
	v_mfma_f32_16x16x32_bf16 v[88:91], v[176:179], v[204:207], v[88:91]
	v_mfma_f32_16x16x32_bf16 v[80:83], v[168:171], v[212:215], v[80:83]
	v_mfma_f32_16x16x32_bf16 v[72:75], v[176:179], v[212:215], v[72:75]
	v_mfma_f32_16x16x32_bf16 v[68:71], v[168:171], v[220:223], v[68:71]
	v_mfma_f32_16x16x32_bf16 v[64:67], v[176:179], v[220:223], v[64:67]
	s_setprio 0
	s_barrier
	s_add_i32 s46, s46, s31
	v_lshl_add_u64 v[142:143], s[22:23], 0, v[134:135]
	s_mov_b32 m0, s46
	ds_read_b128 v[180:183], v146 offset:16384
	ds_read_b128 v[184:187], v146 offset:17408
	ds_read_b128 v[188:191], v146 offset:18432
	ds_read_b128 v[204:207], v146 offset:19456
	ds_read_b128 v[208:211], v146 offset:20480
	ds_read_b128 v[212:215], v146 offset:21504
	ds_read_b128 v[216:219], v146 offset:22528
	ds_read_b128 v[220:223], v146 offset:23552
	global_load_lds_dwordx4 v[142:143], off
	s_add_i32 m0, s46, 0x2000
	s_add_u32 s46, s22, 0x20000
	v_lshl_add_u64 v[192:193], s[22:23], 0, v[130:131]
	s_addc_u32 s47, s23, 0
	s_add_i32 s50, s50, s31
	global_load_lds_dwordx4 v[192:193], off
	v_lshl_add_u64 v[196:197], s[46:47], 0, v[134:135]
	s_mov_b32 m0, s50
	v_lshl_add_u64 v[198:199], s[36:37], 0, v[132:133]
	global_load_lds_dwordx4 v[196:197], off
	s_add_i32 m0, s50, 0x2000
	v_lshl_add_u64 v[196:197], s[46:47], 0, v[130:131]
	global_load_lds_dwordx4 v[196:197], off
	s_mov_b32 m0, s38
	v_lshl_add_u64 v[196:197], s[36:37], 0, v[136:137]
	global_load_lds_dwordx4 v[196:197], off
	s_mov_b32 m0, s39
	s_nop 0
	global_load_lds_dwordx4 v[198:199], off
	s_waitcnt vmcnt(8) lgkmcnt(0)
	s_barrier
	s_setprio 1
	v_mfma_f32_16x16x32_bf16 v[60:63], v[148:151], v[180:183], v[60:63]
	v_mfma_f32_16x16x32_bf16 v[56:59], v[156:159], v[180:183], v[56:59]
	v_mfma_f32_16x16x32_bf16 v[52:55], v[148:151], v[188:191], v[52:55]
	v_mfma_f32_16x16x32_bf16 v[44:47], v[156:159], v[188:191], v[44:47]
	v_mfma_f32_16x16x32_bf16 v[36:39], v[148:151], v[208:211], v[36:39]
	v_mfma_f32_16x16x32_bf16 v[28:31], v[156:159], v[208:211], v[28:31]
	v_mfma_f32_16x16x32_bf16 v[20:23], v[148:151], v[216:219], v[20:23]
	v_mfma_f32_16x16x32_bf16 v[12:15], v[156:159], v[216:219], v[12:15]
	v_mfma_f32_16x16x32_bf16 v[60:63], v[152:155], v[184:187], v[60:63]
	v_mfma_f32_16x16x32_bf16 v[56:59], v[160:163], v[184:187], v[56:59]
	v_mfma_f32_16x16x32_bf16 v[52:55], v[152:155], v[204:207], v[52:55]
	v_mfma_f32_16x16x32_bf16 v[44:47], v[160:163], v[204:207], v[44:47]
	v_mfma_f32_16x16x32_bf16 v[36:39], v[152:155], v[212:215], v[36:39]
	v_mfma_f32_16x16x32_bf16 v[28:31], v[160:163], v[212:215], v[28:31]
	v_mfma_f32_16x16x32_bf16 v[20:23], v[152:155], v[220:223], v[20:23]
	v_mfma_f32_16x16x32_bf16 v[12:15], v[160:163], v[220:223], v[12:15]
	v_mfma_f32_16x16x32_bf16 v[48:51], v[164:167], v[180:183], v[48:51]
	v_mfma_f32_16x16x32_bf16 v[40:43], v[172:175], v[180:183], v[40:43]
	v_mfma_f32_16x16x32_bf16 v[32:35], v[164:167], v[188:191], v[32:35]
	v_mfma_f32_16x16x32_bf16 v[24:27], v[172:175], v[188:191], v[24:27]
	v_mfma_f32_16x16x32_bf16 v[16:19], v[164:167], v[208:211], v[16:19]
	v_mfma_f32_16x16x32_bf16 v[8:11], v[172:175], v[208:211], v[8:11]
	v_mfma_f32_16x16x32_bf16 v[4:7], v[164:167], v[216:219], v[4:7]
	v_mfma_f32_16x16x32_bf16 v[0:3], v[172:175], v[216:219], v[0:3]
	v_mfma_f32_16x16x32_bf16 v[48:51], v[168:171], v[184:187], v[48:51]
	v_mfma_f32_16x16x32_bf16 v[40:43], v[176:179], v[184:187], v[40:43]
	v_mfma_f32_16x16x32_bf16 v[32:35], v[168:171], v[204:207], v[32:35]
	v_mfma_f32_16x16x32_bf16 v[24:27], v[176:179], v[204:207], v[24:27]
	v_mfma_f32_16x16x32_bf16 v[16:19], v[168:171], v[212:215], v[16:19]
	v_mfma_f32_16x16x32_bf16 v[8:11], v[176:179], v[212:215], v[8:11]
	v_mfma_f32_16x16x32_bf16 v[4:7], v[168:171], v[220:223], v[4:7]
	v_mfma_f32_16x16x32_bf16 v[0:3], v[176:179], v[220:223], v[0:3]
	s_setprio 0
	s_barrier
	s_add_i32 s46, 0, 0x18000
	v_add_u32_e32 v147, s46, v145
	s_add_i32 s47, 0, 0x1c000
	ds_read_b128 v[148:151], v147
	ds_read_b128 v[152:155], v147 offset:1024
	ds_read_b128 v[156:159], v147 offset:2048
	ds_read_b128 v[160:163], v147 offset:3072
	v_add_u32_e32 v147, s47, v145
	ds_read_b128 v[164:167], v147
	ds_read_b128 v[168:171], v147 offset:1024
	ds_read_b128 v[172:175], v147 offset:2048
	ds_read_b128 v[176:179], v147 offset:3072
	s_add_u32 s36, s36, 0x20000
	s_addc_u32 s37, s37, 0
	s_mov_b32 m0, s40
	v_lshl_add_u64 v[200:201], s[36:37], 0, v[136:137]
	ds_read_b128 v[180:183], v146 offset:32768
	ds_read_b128 v[184:187], v146 offset:33792
	ds_read_b128 v[188:191], v146 offset:34816
	ds_read_b128 v[204:207], v146 offset:35840
	ds_read_b128 v[208:211], v146 offset:36864
	ds_read_b128 v[212:215], v146 offset:37888
	ds_read_b128 v[216:219], v146 offset:38912
	ds_read_b128 v[220:223], v146 offset:39936
	global_load_lds_dwordx4 v[200:201], off
	s_mov_b32 m0, s41
	v_lshl_add_u64 v[200:201], s[36:37], 0, v[132:133]
	global_load_lds_dwordx4 v[200:201], off
	s_waitcnt vmcnt(8) lgkmcnt(0)
	s_barrier
	s_setprio 1
	v_mfma_f32_16x16x32_bf16 v[126:129], v[148:151], v[180:183], v[126:129]
	v_mfma_f32_16x16x32_bf16 v[122:125], v[156:159], v[180:183], v[122:125]
	v_mfma_f32_16x16x32_bf16 v[118:121], v[148:151], v[188:191], v[118:121]
	v_mfma_f32_16x16x32_bf16 v[110:113], v[156:159], v[188:191], v[110:113]
	v_mfma_f32_16x16x32_bf16 v[102:105], v[148:151], v[208:211], v[102:105]
	v_mfma_f32_16x16x32_bf16 v[92:95], v[156:159], v[208:211], v[92:95]
	v_mfma_f32_16x16x32_bf16 v[84:87], v[148:151], v[216:219], v[84:87]
	v_mfma_f32_16x16x32_bf16 v[76:79], v[156:159], v[216:219], v[76:79]
	v_mfma_f32_16x16x32_bf16 v[126:129], v[152:155], v[184:187], v[126:129]
	v_mfma_f32_16x16x32_bf16 v[122:125], v[160:163], v[184:187], v[122:125]
	v_mfma_f32_16x16x32_bf16 v[118:121], v[152:155], v[204:207], v[118:121]
	v_mfma_f32_16x16x32_bf16 v[110:113], v[160:163], v[204:207], v[110:113]
	v_mfma_f32_16x16x32_bf16 v[102:105], v[152:155], v[212:215], v[102:105]
	v_mfma_f32_16x16x32_bf16 v[92:95], v[160:163], v[212:215], v[92:95]
	v_mfma_f32_16x16x32_bf16 v[84:87], v[152:155], v[220:223], v[84:87]
	v_mfma_f32_16x16x32_bf16 v[76:79], v[160:163], v[220:223], v[76:79]
	v_mfma_f32_16x16x32_bf16 v[114:117], v[164:167], v[180:183], v[114:117]
	v_mfma_f32_16x16x32_bf16 v[106:109], v[172:175], v[180:183], v[106:109]
	v_mfma_f32_16x16x32_bf16 v[98:101], v[164:167], v[188:191], v[98:101]
	v_mfma_f32_16x16x32_bf16 v[88:91], v[172:175], v[188:191], v[88:91]
	v_mfma_f32_16x16x32_bf16 v[80:83], v[164:167], v[208:211], v[80:83]
	v_mfma_f32_16x16x32_bf16 v[72:75], v[172:175], v[208:211], v[72:75]
	v_mfma_f32_16x16x32_bf16 v[68:71], v[164:167], v[216:219], v[68:71]
	v_mfma_f32_16x16x32_bf16 v[64:67], v[172:175], v[216:219], v[64:67]
	v_mfma_f32_16x16x32_bf16 v[114:117], v[168:171], v[184:187], v[114:117]
	v_mfma_f32_16x16x32_bf16 v[106:109], v[176:179], v[184:187], v[106:109]
	v_mfma_f32_16x16x32_bf16 v[98:101], v[168:171], v[204:207], v[98:101]
	v_mfma_f32_16x16x32_bf16 v[88:91], v[176:179], v[204:207], v[88:91]
	v_mfma_f32_16x16x32_bf16 v[80:83], v[168:171], v[212:215], v[80:83]
	v_mfma_f32_16x16x32_bf16 v[72:75], v[176:179], v[212:215], v[72:75]
	v_mfma_f32_16x16x32_bf16 v[68:71], v[168:171], v[220:223], v[68:71]
	v_mfma_f32_16x16x32_bf16 v[64:67], v[176:179], v[220:223], v[64:67]
	s_setprio 0
	s_barrier
	s_add_i32 s36, s46, s31
	v_lshl_add_u64 v[142:143], v[142:143], 0, s[82:83]
	s_mov_b32 m0, s36
	ds_read_b128 v[180:183], v146 offset:49152
	ds_read_b128 v[184:187], v146 offset:50176
	ds_read_b128 v[188:191], v146 offset:51200
	ds_read_b128 v[204:207], v146 offset:52224
	ds_read_b128 v[208:211], v146 offset:53248
	ds_read_b128 v[212:215], v146 offset:54272
	ds_read_b128 v[216:219], v146 offset:55296
	ds_read_b128 v[220:223], v146 offset:56320
	global_load_lds_dwordx4 v[142:143], off
	s_add_i32 m0, s36, 0x2000
	s_add_u32 s22, s22, 0x20080
	v_lshl_add_u64 v[142:143], v[192:193], 0, s[82:83]
	s_addc_u32 s23, s23, 0
	s_add_i32 s36, s47, s31
	global_load_lds_dwordx4 v[142:143], off
	s_mov_b32 m0, s36
	v_lshl_add_u64 v[142:143], s[22:23], 0, v[134:135]
	global_load_lds_dwordx4 v[142:143], off
	s_add_i32 m0, s36, 0x2000
	v_lshl_add_u64 v[142:143], s[22:23], 0, v[130:131]
	global_load_lds_dwordx4 v[142:143], off
	s_mov_b32 m0, s42
	v_lshl_add_u64 v[142:143], v[196:197], 0, s[82:83]
	global_load_lds_dwordx4 v[142:143], off
	s_mov_b32 m0, s43
	v_lshl_add_u64 v[142:143], v[198:199], 0, s[82:83]
	global_load_lds_dwordx4 v[142:143], off
	s_waitcnt vmcnt(8) lgkmcnt(0)
	s_barrier
	s_setprio 1
	v_mfma_f32_16x16x32_bf16 v[60:63], v[148:151], v[180:183], v[60:63]
	v_mfma_f32_16x16x32_bf16 v[56:59], v[156:159], v[180:183], v[56:59]
	v_mfma_f32_16x16x32_bf16 v[52:55], v[148:151], v[188:191], v[52:55]
	v_mfma_f32_16x16x32_bf16 v[44:47], v[156:159], v[188:191], v[44:47]
	v_mfma_f32_16x16x32_bf16 v[36:39], v[148:151], v[208:211], v[36:39]
	v_mfma_f32_16x16x32_bf16 v[28:31], v[156:159], v[208:211], v[28:31]
	v_mfma_f32_16x16x32_bf16 v[20:23], v[148:151], v[216:219], v[20:23]
	v_mfma_f32_16x16x32_bf16 v[12:15], v[156:159], v[216:219], v[12:15]
	v_mfma_f32_16x16x32_bf16 v[60:63], v[152:155], v[184:187], v[60:63]
	v_mfma_f32_16x16x32_bf16 v[56:59], v[160:163], v[184:187], v[56:59]
	v_mfma_f32_16x16x32_bf16 v[52:55], v[152:155], v[204:207], v[52:55]
	v_mfma_f32_16x16x32_bf16 v[44:47], v[160:163], v[204:207], v[44:47]
	v_mfma_f32_16x16x32_bf16 v[36:39], v[152:155], v[212:215], v[36:39]
	v_mfma_f32_16x16x32_bf16 v[28:31], v[160:163], v[212:215], v[28:31]
	v_mfma_f32_16x16x32_bf16 v[20:23], v[152:155], v[220:223], v[20:23]
	v_mfma_f32_16x16x32_bf16 v[12:15], v[160:163], v[220:223], v[12:15]
	v_mfma_f32_16x16x32_bf16 v[48:51], v[164:167], v[180:183], v[48:51]
	v_mfma_f32_16x16x32_bf16 v[40:43], v[172:175], v[180:183], v[40:43]
	v_mfma_f32_16x16x32_bf16 v[32:35], v[164:167], v[188:191], v[32:35]
	v_mfma_f32_16x16x32_bf16 v[24:27], v[172:175], v[188:191], v[24:27]
	v_mfma_f32_16x16x32_bf16 v[16:19], v[164:167], v[208:211], v[16:19]
	v_mfma_f32_16x16x32_bf16 v[8:11], v[172:175], v[208:211], v[8:11]
	v_mfma_f32_16x16x32_bf16 v[4:7], v[164:167], v[216:219], v[4:7]
	v_mfma_f32_16x16x32_bf16 v[0:3], v[172:175], v[216:219], v[0:3]
	v_mfma_f32_16x16x32_bf16 v[48:51], v[168:171], v[184:187], v[48:51]
	v_mfma_f32_16x16x32_bf16 v[40:43], v[176:179], v[184:187], v[40:43]
	v_mfma_f32_16x16x32_bf16 v[32:35], v[168:171], v[204:207], v[32:35]
	v_mfma_f32_16x16x32_bf16 v[24:27], v[176:179], v[204:207], v[24:27]
	v_mfma_f32_16x16x32_bf16 v[16:19], v[168:171], v[212:215], v[16:19]
	v_mfma_f32_16x16x32_bf16 v[8:11], v[176:179], v[212:215], v[8:11]
	v_mfma_f32_16x16x32_bf16 v[4:7], v[168:171], v[220:223], v[4:7]
	v_mfma_f32_16x16x32_bf16 v[0:3], v[176:179], v[220:223], v[0:3]
	s_setprio 0
	s_barrier
	s_add_i32 s54, s54, 2
	s_add_u32 s20, s20, 0x100
	s_addc_u32 s21, s21, 0
	s_add_u32 s13, s13, 0x100
	s_addc_u32 s19, s19, 0
	s_cmp_gt_u32 s54, 5
	s_cbranch_scc0 .LBB0_437
	s_and_b64 vcc, exec, s[10:11]
	s_cbranch_vccz .LBB0_440
	s_barrier

.LBB0_514:
	s_add_u32 s18, s16, 0xfff00080
	s_addc_u32 s19, s17, -1
	s_add_i32 s46, 0, 0x10000
	s_cmp_eq_u32 s52, 60
	s_cselect_b32 s21, s11, s19
	s_cselect_b32 s20, s10, s18
	v_add_u32_e32 v142, s46, v145
	s_cselect_b32 s19, s13, s49
	s_cselect_b32 s18, s12, s48
	s_add_i32 s50, 0, 0x14000
	ds_read_b128 v[148:151], v142
	ds_read_b128 v[152:155], v142 offset:1024
	ds_read_b128 v[156:159], v142 offset:2048
	ds_read_b128 v[160:163], v142 offset:3072
	v_add_u32_e32 v142, s50, v145
	ds_read_b128 v[164:167], v142
	ds_read_b128 v[168:171], v142 offset:1024
	ds_read_b128 v[172:175], v142 offset:2048
	ds_read_b128 v[176:179], v142 offset:3072
	v_lshl_add_u64 v[142:143], s[16:17], 0, v[138:139]
	s_add_i32 m0, s31, 0xc000
	ds_read_b128 v[180:183], v146
	ds_read_b128 v[184:187], v146 offset:1024
	ds_read_b128 v[188:191], v146 offset:2048
	ds_read_b128 v[204:207], v146 offset:3072
	ds_read_b128 v[208:211], v146 offset:4096
	ds_read_b128 v[212:215], v146 offset:5120
	ds_read_b128 v[216:219], v146 offset:6144
	ds_read_b128 v[220:223], v146 offset:7168
	global_load_lds_dwordx4 v[142:143], off
	s_add_i32 m0, s31, 0xe000
	v_lshl_add_u64 v[142:143], s[16:17], 0, v[140:141]
	global_load_lds_dwordx4 v[142:143], off
	s_waitcnt vmcnt(8) lgkmcnt(0)
	s_barrier
	s_setprio 1
	v_mfma_f32_16x16x32_bf16 v[126:129], v[148:151], v[180:183], v[126:129]
	v_mfma_f32_16x16x32_bf16 v[122:125], v[156:159], v[180:183], v[122:125]
	v_mfma_f32_16x16x32_bf16 v[118:121], v[148:151], v[188:191], v[118:121]
	v_mfma_f32_16x16x32_bf16 v[110:113], v[156:159], v[188:191], v[110:113]
	v_mfma_f32_16x16x32_bf16 v[102:105], v[148:151], v[208:211], v[102:105]
	v_mfma_f32_16x16x32_bf16 v[92:95], v[156:159], v[208:211], v[92:95]
	v_mfma_f32_16x16x32_bf16 v[84:87], v[148:151], v[216:219], v[84:87]
	v_mfma_f32_16x16x32_bf16 v[76:79], v[156:159], v[216:219], v[76:79]
	v_mfma_f32_16x16x32_bf16 v[126:129], v[152:155], v[184:187], v[126:129]
	v_mfma_f32_16x16x32_bf16 v[122:125], v[160:163], v[184:187], v[122:125]
	v_mfma_f32_16x16x32_bf16 v[118:121], v[152:155], v[204:207], v[118:121]
	v_mfma_f32_16x16x32_bf16 v[110:113], v[160:163], v[204:207], v[110:113]
	v_mfma_f32_16x16x32_bf16 v[102:105], v[152:155], v[212:215], v[102:105]
	v_mfma_f32_16x16x32_bf16 v[92:95], v[160:163], v[212:215], v[92:95]
	v_mfma_f32_16x16x32_bf16 v[84:87], v[152:155], v[220:223], v[84:87]
	v_mfma_f32_16x16x32_bf16 v[76:79], v[160:163], v[220:223], v[76:79]
	v_mfma_f32_16x16x32_bf16 v[114:117], v[164:167], v[180:183], v[114:117]
	v_mfma_f32_16x16x32_bf16 v[106:109], v[172:175], v[180:183], v[106:109]
	v_mfma_f32_16x16x32_bf16 v[98:101], v[164:167], v[188:191], v[98:101]
	v_mfma_f32_16x16x32_bf16 v[88:91], v[172:175], v[188:191], v[88:91]
	v_mfma_f32_16x16x32_bf16 v[80:83], v[164:167], v[208:211], v[80:83]
	v_mfma_f32_16x16x32_bf16 v[72:75], v[172:175], v[208:211], v[72:75]
	v_mfma_f32_16x16x32_bf16 v[68:71], v[164:167], v[216:219], v[68:71]
	v_mfma_f32_16x16x32_bf16 v[64:67], v[172:175], v[216:219], v[64:67]
	v_mfma_f32_16x16x32_bf16 v[114:117], v[168:171], v[184:187], v[114:117]
	v_mfma_f32_16x16x32_bf16 v[106:109], v[176:179], v[184:187], v[106:109]
	v_mfma_f32_16x16x32_bf16 v[98:101], v[168:171], v[204:207], v[98:101]
	v_mfma_f32_16x16x32_bf16 v[88:91], v[176:179], v[204:207], v[88:91]
	v_mfma_f32_16x16x32_bf16 v[80:83], v[168:171], v[212:215], v[80:83]
	v_mfma_f32_16x16x32_bf16 v[72:75], v[176:179], v[212:215], v[72:75]
	v_mfma_f32_16x16x32_bf16 v[68:71], v[168:171], v[220:223], v[68:71]
	v_mfma_f32_16x16x32_bf16 v[64:67], v[176:179], v[220:223], v[64:67]
	s_setprio 0
	s_barrier
	s_add_i32 s46, s46, s29
	v_lshl_add_u64 v[142:143], s[18:19], 0, v[134:135]
	s_mov_b32 m0, s46
	ds_read_b128 v[180:183], v146 offset:16384
	ds_read_b128 v[184:187], v146 offset:17408
	ds_read_b128 v[188:191], v146 offset:18432
	ds_read_b128 v[204:207], v146 offset:19456
	ds_read_b128 v[208:211], v146 offset:20480
	ds_read_b128 v[212:215], v146 offset:21504
	ds_read_b128 v[216:219], v146 offset:22528
	ds_read_b128 v[220:223], v146 offset:23552
	global_load_lds_dwordx4 v[142:143], off
	s_add_i32 m0, s46, 0x2000
	s_add_u32 s46, s18, 0x600000
	v_lshl_add_u64 v[192:193], s[18:19], 0, v[130:131]
	s_addc_u32 s47, s19, 0
	s_add_i32 s50, s50, s29
	global_load_lds_dwordx4 v[192:193], off
	v_lshl_add_u64 v[196:197], s[46:47], 0, v[134:135]
	s_mov_b32 m0, s50
	v_lshl_add_u64 v[198:199], s[20:21], 0, v[132:133]
	global_load_lds_dwordx4 v[196:197], off
	s_add_i32 m0, s50, 0x2000
	v_lshl_add_u64 v[196:197], s[46:47], 0, v[130:131]
	global_load_lds_dwordx4 v[196:197], off
	s_mov_b32 m0, s31
	v_lshl_add_u64 v[196:197], s[20:21], 0, v[136:137]
	global_load_lds_dwordx4 v[196:197], off
	s_mov_b32 m0, s36
	s_nop 0
	global_load_lds_dwordx4 v[198:199], off
	s_waitcnt vmcnt(8) lgkmcnt(0)
	s_barrier
	s_setprio 1
	v_mfma_f32_16x16x32_bf16 v[60:63], v[148:151], v[180:183], v[60:63]
	v_mfma_f32_16x16x32_bf16 v[56:59], v[156:159], v[180:183], v[56:59]
	v_mfma_f32_16x16x32_bf16 v[52:55], v[148:151], v[188:191], v[52:55]
	v_mfma_f32_16x16x32_bf16 v[44:47], v[156:159], v[188:191], v[44:47]
	v_mfma_f32_16x16x32_bf16 v[36:39], v[148:151], v[208:211], v[36:39]
	v_mfma_f32_16x16x32_bf16 v[28:31], v[156:159], v[208:211], v[28:31]
	v_mfma_f32_16x16x32_bf16 v[20:23], v[148:151], v[216:219], v[20:23]
	v_mfma_f32_16x16x32_bf16 v[12:15], v[156:159], v[216:219], v[12:15]
	v_mfma_f32_16x16x32_bf16 v[60:63], v[152:155], v[184:187], v[60:63]
	v_mfma_f32_16x16x32_bf16 v[56:59], v[160:163], v[184:187], v[56:59]
	v_mfma_f32_16x16x32_bf16 v[52:55], v[152:155], v[204:207], v[52:55]
	v_mfma_f32_16x16x32_bf16 v[44:47], v[160:163], v[204:207], v[44:47]
	v_mfma_f32_16x16x32_bf16 v[36:39], v[152:155], v[212:215], v[36:39]
	v_mfma_f32_16x16x32_bf16 v[28:31], v[160:163], v[212:215], v[28:31]
	v_mfma_f32_16x16x32_bf16 v[20:23], v[152:155], v[220:223], v[20:23]
	v_mfma_f32_16x16x32_bf16 v[12:15], v[160:163], v[220:223], v[12:15]
	v_mfma_f32_16x16x32_bf16 v[48:51], v[164:167], v[180:183], v[48:51]
	v_mfma_f32_16x16x32_bf16 v[40:43], v[172:175], v[180:183], v[40:43]
	v_mfma_f32_16x16x32_bf16 v[32:35], v[164:167], v[188:191], v[32:35]
	v_mfma_f32_16x16x32_bf16 v[24:27], v[172:175], v[188:191], v[24:27]
	v_mfma_f32_16x16x32_bf16 v[16:19], v[164:167], v[208:211], v[16:19]
	v_mfma_f32_16x16x32_bf16 v[8:11], v[172:175], v[208:211], v[8:11]
	v_mfma_f32_16x16x32_bf16 v[4:7], v[164:167], v[216:219], v[4:7]
	v_mfma_f32_16x16x32_bf16 v[0:3], v[172:175], v[216:219], v[0:3]
	v_mfma_f32_16x16x32_bf16 v[48:51], v[168:171], v[184:187], v[48:51]
	v_mfma_f32_16x16x32_bf16 v[40:43], v[176:179], v[184:187], v[40:43]
	v_mfma_f32_16x16x32_bf16 v[32:35], v[168:171], v[204:207], v[32:35]
	v_mfma_f32_16x16x32_bf16 v[24:27], v[176:179], v[204:207], v[24:27]
	v_mfma_f32_16x16x32_bf16 v[16:19], v[168:171], v[212:215], v[16:19]
	v_mfma_f32_16x16x32_bf16 v[8:11], v[176:179], v[212:215], v[8:11]
	v_mfma_f32_16x16x32_bf16 v[4:7], v[168:171], v[220:223], v[4:7]
	v_mfma_f32_16x16x32_bf16 v[0:3], v[176:179], v[220:223], v[0:3]
	s_setprio 0
	s_barrier
	s_add_i32 s46, 0, 0x18000
	v_add_u32_e32 v147, s46, v145
	s_add_i32 s47, 0, 0x1c000
	ds_read_b128 v[148:151], v147
	ds_read_b128 v[152:155], v147 offset:1024
	ds_read_b128 v[156:159], v147 offset:2048
	ds_read_b128 v[160:163], v147 offset:3072
	v_add_u32_e32 v147, s47, v145
	ds_read_b128 v[164:167], v147
	ds_read_b128 v[168:171], v147 offset:1024
	ds_read_b128 v[172:175], v147 offset:2048
	ds_read_b128 v[176:179], v147 offset:3072
	s_add_u32 s20, s20, 0x100000
	s_addc_u32 s21, s21, 0
	s_mov_b32 m0, s37
	v_lshl_add_u64 v[200:201], s[20:21], 0, v[136:137]
	ds_read_b128 v[180:183], v146 offset:32768
	ds_read_b128 v[184:187], v146 offset:33792
	ds_read_b128 v[188:191], v146 offset:34816
	ds_read_b128 v[204:207], v146 offset:35840
	ds_read_b128 v[208:211], v146 offset:36864
	ds_read_b128 v[212:215], v146 offset:37888
	ds_read_b128 v[216:219], v146 offset:38912
	ds_read_b128 v[220:223], v146 offset:39936
	global_load_lds_dwordx4 v[200:201], off
	s_mov_b32 m0, s38
	v_lshl_add_u64 v[200:201], s[20:21], 0, v[132:133]
	global_load_lds_dwordx4 v[200:201], off
	s_waitcnt vmcnt(8) lgkmcnt(0)
	s_barrier
	s_setprio 1
	v_mfma_f32_16x16x32_bf16 v[126:129], v[148:151], v[180:183], v[126:129]
	v_mfma_f32_16x16x32_bf16 v[122:125], v[156:159], v[180:183], v[122:125]
	v_mfma_f32_16x16x32_bf16 v[118:121], v[148:151], v[188:191], v[118:121]
	v_mfma_f32_16x16x32_bf16 v[110:113], v[156:159], v[188:191], v[110:113]
	v_mfma_f32_16x16x32_bf16 v[102:105], v[148:151], v[208:211], v[102:105]
	v_mfma_f32_16x16x32_bf16 v[92:95], v[156:159], v[208:211], v[92:95]
	v_mfma_f32_16x16x32_bf16 v[84:87], v[148:151], v[216:219], v[84:87]
	v_mfma_f32_16x16x32_bf16 v[76:79], v[156:159], v[216:219], v[76:79]
	v_mfma_f32_16x16x32_bf16 v[126:129], v[152:155], v[184:187], v[126:129]
	v_mfma_f32_16x16x32_bf16 v[122:125], v[160:163], v[184:187], v[122:125]
	v_mfma_f32_16x16x32_bf16 v[118:121], v[152:155], v[204:207], v[118:121]
	v_mfma_f32_16x16x32_bf16 v[110:113], v[160:163], v[204:207], v[110:113]
	v_mfma_f32_16x16x32_bf16 v[102:105], v[152:155], v[212:215], v[102:105]
	v_mfma_f32_16x16x32_bf16 v[92:95], v[160:163], v[212:215], v[92:95]
	v_mfma_f32_16x16x32_bf16 v[84:87], v[152:155], v[220:223], v[84:87]
	v_mfma_f32_16x16x32_bf16 v[76:79], v[160:163], v[220:223], v[76:79]
	v_mfma_f32_16x16x32_bf16 v[114:117], v[164:167], v[180:183], v[114:117]
	v_mfma_f32_16x16x32_bf16 v[106:109], v[172:175], v[180:183], v[106:109]
	v_mfma_f32_16x16x32_bf16 v[98:101], v[164:167], v[188:191], v[98:101]
	v_mfma_f32_16x16x32_bf16 v[88:91], v[172:175], v[188:191], v[88:91]
	v_mfma_f32_16x16x32_bf16 v[80:83], v[164:167], v[208:211], v[80:83]
	v_mfma_f32_16x16x32_bf16 v[72:75], v[172:175], v[208:211], v[72:75]
	v_mfma_f32_16x16x32_bf16 v[68:71], v[164:167], v[216:219], v[68:71]
	v_mfma_f32_16x16x32_bf16 v[64:67], v[172:175], v[216:219], v[64:67]
	v_mfma_f32_16x16x32_bf16 v[114:117], v[168:171], v[184:187], v[114:117]
	v_mfma_f32_16x16x32_bf16 v[106:109], v[176:179], v[184:187], v[106:109]
	v_mfma_f32_16x16x32_bf16 v[98:101], v[168:171], v[204:207], v[98:101]
	v_mfma_f32_16x16x32_bf16 v[88:91], v[176:179], v[204:207], v[88:91]
	v_mfma_f32_16x16x32_bf16 v[80:83], v[168:171], v[212:215], v[80:83]
	v_mfma_f32_16x16x32_bf16 v[72:75], v[176:179], v[212:215], v[72:75]
	v_mfma_f32_16x16x32_bf16 v[68:71], v[168:171], v[220:223], v[68:71]
	v_mfma_f32_16x16x32_bf16 v[64:67], v[176:179], v[220:223], v[64:67]
	s_setprio 0
	s_barrier
	s_add_i32 s20, s46, s29
	v_lshl_add_u64 v[142:143], v[142:143], 0, s[82:83]
	s_mov_b32 m0, s20
	ds_read_b128 v[180:183], v146 offset:49152
	ds_read_b128 v[184:187], v146 offset:50176
	ds_read_b128 v[188:191], v146 offset:51200
	ds_read_b128 v[204:207], v146 offset:52224
	ds_read_b128 v[208:211], v146 offset:53248
	ds_read_b128 v[212:215], v146 offset:54272
	ds_read_b128 v[216:219], v146 offset:55296
	ds_read_b128 v[220:223], v146 offset:56320
	global_load_lds_dwordx4 v[142:143], off
	s_add_i32 m0, s20, 0x2000
	s_add_u32 s18, s18, 0x600080
	v_lshl_add_u64 v[142:143], v[192:193], 0, s[82:83]
	s_addc_u32 s19, s19, 0
	s_add_i32 s20, s47, s29
	global_load_lds_dwordx4 v[142:143], off
	s_mov_b32 m0, s20
	v_lshl_add_u64 v[142:143], s[18:19], 0, v[134:135]
	global_load_lds_dwordx4 v[142:143], off
	s_add_i32 m0, s20, 0x2000
	v_lshl_add_u64 v[142:143], s[18:19], 0, v[130:131]
	global_load_lds_dwordx4 v[142:143], off
	s_mov_b32 m0, s39
	v_lshl_add_u64 v[142:143], v[196:197], 0, s[82:83]
	global_load_lds_dwordx4 v[142:143], off
	s_mov_b32 m0, s40
	v_lshl_add_u64 v[142:143], v[198:199], 0, s[82:83]
	global_load_lds_dwordx4 v[142:143], off
	s_waitcnt vmcnt(8) lgkmcnt(0)
	s_barrier
	s_setprio 1
	v_mfma_f32_16x16x32_bf16 v[60:63], v[148:151], v[180:183], v[60:63]
	v_mfma_f32_16x16x32_bf16 v[56:59], v[156:159], v[180:183], v[56:59]
	v_mfma_f32_16x16x32_bf16 v[52:55], v[148:151], v[188:191], v[52:55]
	v_mfma_f32_16x16x32_bf16 v[44:47], v[156:159], v[188:191], v[44:47]
	v_mfma_f32_16x16x32_bf16 v[36:39], v[148:151], v[208:211], v[36:39]
	v_mfma_f32_16x16x32_bf16 v[28:31], v[156:159], v[208:211], v[28:31]
	v_mfma_f32_16x16x32_bf16 v[20:23], v[148:151], v[216:219], v[20:23]
	v_mfma_f32_16x16x32_bf16 v[12:15], v[156:159], v[216:219], v[12:15]
	v_mfma_f32_16x16x32_bf16 v[60:63], v[152:155], v[184:187], v[60:63]
	v_mfma_f32_16x16x32_bf16 v[56:59], v[160:163], v[184:187], v[56:59]
	v_mfma_f32_16x16x32_bf16 v[52:55], v[152:155], v[204:207], v[52:55]
	v_mfma_f32_16x16x32_bf16 v[44:47], v[160:163], v[204:207], v[44:47]
	v_mfma_f32_16x16x32_bf16 v[36:39], v[152:155], v[212:215], v[36:39]
	v_mfma_f32_16x16x32_bf16 v[28:31], v[160:163], v[212:215], v[28:31]
	v_mfma_f32_16x16x32_bf16 v[20:23], v[152:155], v[220:223], v[20:23]
	v_mfma_f32_16x16x32_bf16 v[12:15], v[160:163], v[220:223], v[12:15]
	v_mfma_f32_16x16x32_bf16 v[48:51], v[164:167], v[180:183], v[48:51]
	v_mfma_f32_16x16x32_bf16 v[40:43], v[172:175], v[180:183], v[40:43]
	v_mfma_f32_16x16x32_bf16 v[32:35], v[164:167], v[188:191], v[32:35]
	v_mfma_f32_16x16x32_bf16 v[24:27], v[172:175], v[188:191], v[24:27]
	v_mfma_f32_16x16x32_bf16 v[16:19], v[164:167], v[208:211], v[16:19]
	v_mfma_f32_16x16x32_bf16 v[8:11], v[172:175], v[208:211], v[8:11]
	v_mfma_f32_16x16x32_bf16 v[4:7], v[164:167], v[216:219], v[4:7]
	v_mfma_f32_16x16x32_bf16 v[0:3], v[172:175], v[216:219], v[0:3]
	v_mfma_f32_16x16x32_bf16 v[48:51], v[168:171], v[184:187], v[48:51]
	v_mfma_f32_16x16x32_bf16 v[40:43], v[176:179], v[184:187], v[40:43]
	v_mfma_f32_16x16x32_bf16 v[32:35], v[168:171], v[204:207], v[32:35]
	v_mfma_f32_16x16x32_bf16 v[24:27], v[176:179], v[204:207], v[24:27]
	v_mfma_f32_16x16x32_bf16 v[16:19], v[168:171], v[212:215], v[16:19]
	v_mfma_f32_16x16x32_bf16 v[8:11], v[176:179], v[212:215], v[8:11]
	v_mfma_f32_16x16x32_bf16 v[4:7], v[168:171], v[220:223], v[4:7]
	v_mfma_f32_16x16x32_bf16 v[0:3], v[176:179], v[220:223], v[0:3]
	s_setprio 0
	s_barrier
	s_add_i32 s52, s52, 2
	s_add_u32 s16, s16, 0x100
	s_addc_u32 s17, s17, 0
	s_add_u32 s48, s48, 0x100
	s_addc_u32 s49, s49, 0
	s_cmp_gt_u32 s52, 61
	s_cbranch_scc0 .LBB0_514
	s_and_b64 vcc, exec, s[8:9]
	s_cbranch_vccz .LBB0_517
	s_barrier

.LBB0_579:
	s_add_u32 s22, s20, 0x100
	s_addc_u32 s23, s21, 0
	s_add_u32 s36, s15, s20
	s_addc_u32 s37, s49, s21
	s_cmp_eq_u32 s52, 4
	s_cselect_b32 s38, 0, s22
	s_cselect_b32 s39, 0, s23
	s_cselect_b32 s36, s16, s36
	s_cselect_b32 s37, s17, s37
	s_add_u32 s38, s6, s38
	s_addc_u32 s39, s7, s39
	s_add_i32 s46, 0, 0x10000
	v_add_u32_e32 v142, s46, v145
	s_add_i32 s47, 0, 0x14000
	ds_read_b128 v[148:151], v142
	ds_read_b128 v[152:155], v142 offset:1024
	ds_read_b128 v[156:159], v142 offset:2048
	ds_read_b128 v[160:163], v142 offset:3072
	v_add_u32_e32 v142, s47, v145
	ds_read_b128 v[164:167], v142
	ds_read_b128 v[168:171], v142 offset:1024
	ds_read_b128 v[172:175], v142 offset:2048
	ds_read_b128 v[176:179], v142 offset:3072
	v_lshl_add_u64 v[142:143], v[138:139], 0, s[20:21]
	s_add_i32 m0, s19, 0xc000
	ds_read_b128 v[180:183], v146
	ds_read_b128 v[184:187], v146 offset:1024
	ds_read_b128 v[188:191], v146 offset:2048
	ds_read_b128 v[196:199], v146 offset:3072
	ds_read_b128 v[200:203], v146 offset:4096
	ds_read_b128 v[204:207], v146 offset:5120
	ds_read_b128 v[208:211], v146 offset:6144
	ds_read_b128 v[212:215], v146 offset:7168
	global_load_lds_dwordx4 v[142:143], off
	s_add_i32 m0, s19, 0xe000
	v_lshl_add_u64 v[142:143], v[140:141], 0, s[20:21]
	global_load_lds_dwordx4 v[142:143], off
	s_waitcnt vmcnt(8) lgkmcnt(0)
	s_barrier
	s_setprio 1
	v_mfma_f32_16x16x32_bf16 v[126:129], v[148:151], v[180:183], v[126:129]
	v_mfma_f32_16x16x32_bf16 v[122:125], v[156:159], v[180:183], v[122:125]
	v_mfma_f32_16x16x32_bf16 v[118:121], v[148:151], v[188:191], v[118:121]
	v_mfma_f32_16x16x32_bf16 v[110:113], v[156:159], v[188:191], v[110:113]
	v_mfma_f32_16x16x32_bf16 v[102:105], v[148:151], v[200:203], v[102:105]
	v_mfma_f32_16x16x32_bf16 v[92:95], v[156:159], v[200:203], v[92:95]
	v_mfma_f32_16x16x32_bf16 v[84:87], v[148:151], v[208:211], v[84:87]
	v_mfma_f32_16x16x32_bf16 v[76:79], v[156:159], v[208:211], v[76:79]
	v_mfma_f32_16x16x32_bf16 v[126:129], v[152:155], v[184:187], v[126:129]
	v_mfma_f32_16x16x32_bf16 v[122:125], v[160:163], v[184:187], v[122:125]
	v_mfma_f32_16x16x32_bf16 v[118:121], v[152:155], v[196:199], v[118:121]
	v_mfma_f32_16x16x32_bf16 v[110:113], v[160:163], v[196:199], v[110:113]
	v_mfma_f32_16x16x32_bf16 v[102:105], v[152:155], v[204:207], v[102:105]
	v_mfma_f32_16x16x32_bf16 v[92:95], v[160:163], v[204:207], v[92:95]
	v_mfma_f32_16x16x32_bf16 v[84:87], v[152:155], v[212:215], v[84:87]
	v_mfma_f32_16x16x32_bf16 v[76:79], v[160:163], v[212:215], v[76:79]
	v_mfma_f32_16x16x32_bf16 v[114:117], v[164:167], v[180:183], v[114:117]
	v_mfma_f32_16x16x32_bf16 v[106:109], v[172:175], v[180:183], v[106:109]
	v_mfma_f32_16x16x32_bf16 v[98:101], v[164:167], v[188:191], v[98:101]
	v_mfma_f32_16x16x32_bf16 v[88:91], v[172:175], v[188:191], v[88:91]
	v_mfma_f32_16x16x32_bf16 v[80:83], v[164:167], v[200:203], v[80:83]
	v_mfma_f32_16x16x32_bf16 v[72:75], v[172:175], v[200:203], v[72:75]
	v_mfma_f32_16x16x32_bf16 v[68:71], v[164:167], v[208:211], v[68:71]
	v_mfma_f32_16x16x32_bf16 v[64:67], v[172:175], v[208:211], v[64:67]
	v_mfma_f32_16x16x32_bf16 v[114:117], v[168:171], v[184:187], v[114:117]
	v_mfma_f32_16x16x32_bf16 v[106:109], v[176:179], v[184:187], v[106:109]
	v_mfma_f32_16x16x32_bf16 v[98:101], v[168:171], v[196:199], v[98:101]
	v_mfma_f32_16x16x32_bf16 v[88:91], v[176:179], v[196:199], v[88:91]
	v_mfma_f32_16x16x32_bf16 v[80:83], v[168:171], v[204:207], v[80:83]
	v_mfma_f32_16x16x32_bf16 v[72:75], v[176:179], v[204:207], v[72:75]
	v_mfma_f32_16x16x32_bf16 v[68:71], v[168:171], v[212:215], v[68:71]
	v_mfma_f32_16x16x32_bf16 v[64:67], v[176:179], v[212:215], v[64:67]
	s_setprio 0
	s_barrier
	s_add_i32 s20, s46, s29
	v_lshl_add_u64 v[142:143], s[36:37], 0, v[134:135]
	s_mov_b32 m0, s20
	ds_read_b128 v[180:183], v146 offset:16384
	ds_read_b128 v[184:187], v146 offset:17408
	ds_read_b128 v[188:191], v146 offset:18432
	ds_read_b128 v[196:199], v146 offset:19456
	ds_read_b128 v[200:203], v146 offset:20480
	ds_read_b128 v[204:207], v146 offset:21504
	ds_read_b128 v[208:211], v146 offset:22528
	ds_read_b128 v[212:215], v146 offset:23552
	global_load_lds_dwordx4 v[142:143], off
	s_add_i32 m0, s20, 0x2000
	s_add_u32 s20, s36, 0x600000
	v_lshl_add_u64 v[192:193], s[36:37], 0, v[130:131]
	s_addc_u32 s21, s37, 0
	s_add_i32 s46, s47, s29
	global_load_lds_dwordx4 v[192:193], off
	v_lshl_add_u64 v[216:217], s[20:21], 0, v[134:135]
	s_mov_b32 m0, s46
	v_lshl_add_u64 v[218:219], s[38:39], 0, v[132:133]
	global_load_lds_dwordx4 v[216:217], off
	s_add_i32 m0, s46, 0x2000
	v_lshl_add_u64 v[216:217], s[20:21], 0, v[130:131]
	global_load_lds_dwordx4 v[216:217], off
	s_mov_b32 m0, s19
	v_lshl_add_u64 v[216:217], s[38:39], 0, v[136:137]
	global_load_lds_dwordx4 v[216:217], off
	s_mov_b32 m0, s31
	s_nop 0
	global_load_lds_dwordx4 v[218:219], off
	s_waitcnt vmcnt(8) lgkmcnt(0)
	s_barrier
	s_setprio 1
	v_mfma_f32_16x16x32_bf16 v[60:63], v[148:151], v[180:183], v[60:63]
	v_mfma_f32_16x16x32_bf16 v[56:59], v[156:159], v[180:183], v[56:59]
	v_mfma_f32_16x16x32_bf16 v[52:55], v[148:151], v[188:191], v[52:55]
	v_mfma_f32_16x16x32_bf16 v[44:47], v[156:159], v[188:191], v[44:47]
	v_mfma_f32_16x16x32_bf16 v[36:39], v[148:151], v[200:203], v[36:39]
	v_mfma_f32_16x16x32_bf16 v[28:31], v[156:159], v[200:203], v[28:31]
	v_mfma_f32_16x16x32_bf16 v[20:23], v[148:151], v[208:211], v[20:23]
	v_mfma_f32_16x16x32_bf16 v[12:15], v[156:159], v[208:211], v[12:15]
	v_mfma_f32_16x16x32_bf16 v[60:63], v[152:155], v[184:187], v[60:63]
	v_mfma_f32_16x16x32_bf16 v[56:59], v[160:163], v[184:187], v[56:59]
	v_mfma_f32_16x16x32_bf16 v[52:55], v[152:155], v[196:199], v[52:55]
	v_mfma_f32_16x16x32_bf16 v[44:47], v[160:163], v[196:199], v[44:47]
	v_mfma_f32_16x16x32_bf16 v[36:39], v[152:155], v[204:207], v[36:39]
	v_mfma_f32_16x16x32_bf16 v[28:31], v[160:163], v[204:207], v[28:31]
	v_mfma_f32_16x16x32_bf16 v[20:23], v[152:155], v[212:215], v[20:23]
	v_mfma_f32_16x16x32_bf16 v[12:15], v[160:163], v[212:215], v[12:15]
	v_mfma_f32_16x16x32_bf16 v[48:51], v[164:167], v[180:183], v[48:51]
	v_mfma_f32_16x16x32_bf16 v[40:43], v[172:175], v[180:183], v[40:43]
	v_mfma_f32_16x16x32_bf16 v[32:35], v[164:167], v[188:191], v[32:35]
	v_mfma_f32_16x16x32_bf16 v[24:27], v[172:175], v[188:191], v[24:27]
	v_mfma_f32_16x16x32_bf16 v[16:19], v[164:167], v[200:203], v[16:19]
	v_mfma_f32_16x16x32_bf16 v[8:11], v[172:175], v[200:203], v[8:11]
	v_mfma_f32_16x16x32_bf16 v[4:7], v[164:167], v[208:211], v[4:7]
	v_mfma_f32_16x16x32_bf16 v[0:3], v[172:175], v[208:211], v[0:3]
	v_mfma_f32_16x16x32_bf16 v[48:51], v[168:171], v[184:187], v[48:51]
	v_mfma_f32_16x16x32_bf16 v[40:43], v[176:179], v[184:187], v[40:43]
	v_mfma_f32_16x16x32_bf16 v[32:35], v[168:171], v[196:199], v[32:35]
	v_mfma_f32_16x16x32_bf16 v[24:27], v[176:179], v[196:199], v[24:27]
	v_mfma_f32_16x16x32_bf16 v[16:19], v[168:171], v[204:207], v[16:19]
	v_mfma_f32_16x16x32_bf16 v[8:11], v[176:179], v[204:207], v[8:11]
	v_mfma_f32_16x16x32_bf16 v[4:7], v[168:171], v[212:215], v[4:7]
	v_mfma_f32_16x16x32_bf16 v[0:3], v[176:179], v[212:215], v[0:3]
	s_setprio 0
	s_barrier
	s_add_i32 s46, 0, 0x18000
	v_add_u32_e32 v147, s46, v145
	s_add_i32 s47, 0, 0x1c000
	ds_read_b128 v[148:151], v147
	ds_read_b128 v[152:155], v147 offset:1024
	ds_read_b128 v[156:159], v147 offset:2048
	ds_read_b128 v[160:163], v147 offset:3072
	v_add_u32_e32 v147, s47, v145
	ds_read_b128 v[164:167], v147
	ds_read_b128 v[168:171], v147 offset:1024
	ds_read_b128 v[172:175], v147 offset:2048
	ds_read_b128 v[176:179], v147 offset:3072
	s_add_u32 s20, s38, 0x20000
	s_addc_u32 s21, s39, 0
	s_mov_b32 m0, s40
	v_lshl_add_u64 v[220:221], s[20:21], 0, v[136:137]
	ds_read_b128 v[180:183], v146 offset:32768
	ds_read_b128 v[184:187], v146 offset:33792
	ds_read_b128 v[188:191], v146 offset:34816
	ds_read_b128 v[196:199], v146 offset:35840
	ds_read_b128 v[200:203], v146 offset:36864
	ds_read_b128 v[204:207], v146 offset:37888
	ds_read_b128 v[208:211], v146 offset:38912
	ds_read_b128 v[212:215], v146 offset:39936
	global_load_lds_dwordx4 v[220:221], off
	s_mov_b32 m0, s41
	v_lshl_add_u64 v[220:221], s[20:21], 0, v[132:133]
	global_load_lds_dwordx4 v[220:221], off
	s_waitcnt vmcnt(8) lgkmcnt(0)
	s_barrier
	s_setprio 1
	v_mfma_f32_16x16x32_bf16 v[126:129], v[148:151], v[180:183], v[126:129]
	v_mfma_f32_16x16x32_bf16 v[122:125], v[156:159], v[180:183], v[122:125]
	v_mfma_f32_16x16x32_bf16 v[118:121], v[148:151], v[188:191], v[118:121]
	v_mfma_f32_16x16x32_bf16 v[110:113], v[156:159], v[188:191], v[110:113]
	v_mfma_f32_16x16x32_bf16 v[102:105], v[148:151], v[200:203], v[102:105]
	v_mfma_f32_16x16x32_bf16 v[92:95], v[156:159], v[200:203], v[92:95]
	v_mfma_f32_16x16x32_bf16 v[84:87], v[148:151], v[208:211], v[84:87]
	v_mfma_f32_16x16x32_bf16 v[76:79], v[156:159], v[208:211], v[76:79]
	v_mfma_f32_16x16x32_bf16 v[126:129], v[152:155], v[184:187], v[126:129]
	v_mfma_f32_16x16x32_bf16 v[122:125], v[160:163], v[184:187], v[122:125]
	v_mfma_f32_16x16x32_bf16 v[118:121], v[152:155], v[196:199], v[118:121]
	v_mfma_f32_16x16x32_bf16 v[110:113], v[160:163], v[196:199], v[110:113]
	v_mfma_f32_16x16x32_bf16 v[102:105], v[152:155], v[204:207], v[102:105]
	v_mfma_f32_16x16x32_bf16 v[92:95], v[160:163], v[204:207], v[92:95]
	v_mfma_f32_16x16x32_bf16 v[84:87], v[152:155], v[212:215], v[84:87]
	v_mfma_f32_16x16x32_bf16 v[76:79], v[160:163], v[212:215], v[76:79]
	v_mfma_f32_16x16x32_bf16 v[114:117], v[164:167], v[180:183], v[114:117]
	v_mfma_f32_16x16x32_bf16 v[106:109], v[172:175], v[180:183], v[106:109]
	v_mfma_f32_16x16x32_bf16 v[98:101], v[164:167], v[188:191], v[98:101]
	v_mfma_f32_16x16x32_bf16 v[88:91], v[172:175], v[188:191], v[88:91]
	v_mfma_f32_16x16x32_bf16 v[80:83], v[164:167], v[200:203], v[80:83]
	v_mfma_f32_16x16x32_bf16 v[72:75], v[172:175], v[200:203], v[72:75]
	v_mfma_f32_16x16x32_bf16 v[68:71], v[164:167], v[208:211], v[68:71]
	v_mfma_f32_16x16x32_bf16 v[64:67], v[172:175], v[208:211], v[64:67]
	v_mfma_f32_16x16x32_bf16 v[114:117], v[168:171], v[184:187], v[114:117]
	v_mfma_f32_16x16x32_bf16 v[106:109], v[176:179], v[184:187], v[106:109]
	v_mfma_f32_16x16x32_bf16 v[98:101], v[168:171], v[196:199], v[98:101]
	v_mfma_f32_16x16x32_bf16 v[88:91], v[176:179], v[196:199], v[88:91]
	v_mfma_f32_16x16x32_bf16 v[80:83], v[168:171], v[204:207], v[80:83]
	v_mfma_f32_16x16x32_bf16 v[72:75], v[176:179], v[204:207], v[72:75]
	v_mfma_f32_16x16x32_bf16 v[68:71], v[168:171], v[212:215], v[68:71]
	v_mfma_f32_16x16x32_bf16 v[64:67], v[176:179], v[212:215], v[64:67]
	s_setprio 0
	s_barrier
	s_add_i32 s20, s46, s29
	v_lshl_add_u64 v[142:143], v[142:143], 0, s[82:83]
	s_mov_b32 m0, s20
	ds_read_b128 v[180:183], v146 offset:49152
	ds_read_b128 v[184:187], v146 offset:50176
	ds_read_b128 v[188:191], v146 offset:51200
	ds_read_b128 v[196:199], v146 offset:52224
	ds_read_b128 v[200:203], v146 offset:53248
	ds_read_b128 v[204:207], v146 offset:54272
	ds_read_b128 v[208:211], v146 offset:55296
	ds_read_b128 v[212:215], v146 offset:56320
	global_load_lds_dwordx4 v[142:143], off
	s_add_i32 m0, s20, 0x2000
	s_add_u32 s20, s36, 0x600080
	v_lshl_add_u64 v[142:143], v[192:193], 0, s[82:83]
	s_addc_u32 s21, s37, 0
	s_add_i32 s36, s47, s29
	global_load_lds_dwordx4 v[142:143], off
	s_mov_b32 m0, s36
	v_lshl_add_u64 v[142:143], s[20:21], 0, v[134:135]
	global_load_lds_dwordx4 v[142:143], off
	s_add_i32 m0, s36, 0x2000
	v_lshl_add_u64 v[142:143], s[20:21], 0, v[130:131]
	global_load_lds_dwordx4 v[142:143], off
	s_mov_b32 m0, s42
	v_lshl_add_u64 v[142:143], v[216:217], 0, s[82:83]
	global_load_lds_dwordx4 v[142:143], off
	s_mov_b32 m0, s43
	v_lshl_add_u64 v[142:143], v[218:219], 0, s[82:83]
	global_load_lds_dwordx4 v[142:143], off
	s_waitcnt vmcnt(8) lgkmcnt(0)
	s_barrier
	s_setprio 1
	v_mfma_f32_16x16x32_bf16 v[60:63], v[148:151], v[180:183], v[60:63]
	v_mfma_f32_16x16x32_bf16 v[56:59], v[156:159], v[180:183], v[56:59]
	v_mfma_f32_16x16x32_bf16 v[52:55], v[148:151], v[188:191], v[52:55]
	v_mfma_f32_16x16x32_bf16 v[44:47], v[156:159], v[188:191], v[44:47]
	v_mfma_f32_16x16x32_bf16 v[36:39], v[148:151], v[200:203], v[36:39]
	v_mfma_f32_16x16x32_bf16 v[28:31], v[156:159], v[200:203], v[28:31]
	v_mfma_f32_16x16x32_bf16 v[20:23], v[148:151], v[208:211], v[20:23]
	v_mfma_f32_16x16x32_bf16 v[12:15], v[156:159], v[208:211], v[12:15]
	v_mfma_f32_16x16x32_bf16 v[60:63], v[152:155], v[184:187], v[60:63]
	v_mfma_f32_16x16x32_bf16 v[56:59], v[160:163], v[184:187], v[56:59]
	v_mfma_f32_16x16x32_bf16 v[52:55], v[152:155], v[196:199], v[52:55]
	v_mfma_f32_16x16x32_bf16 v[44:47], v[160:163], v[196:199], v[44:47]
	v_mfma_f32_16x16x32_bf16 v[36:39], v[152:155], v[204:207], v[36:39]
	v_mfma_f32_16x16x32_bf16 v[28:31], v[160:163], v[204:207], v[28:31]
	v_mfma_f32_16x16x32_bf16 v[20:23], v[152:155], v[212:215], v[20:23]
	v_mfma_f32_16x16x32_bf16 v[12:15], v[160:163], v[212:215], v[12:15]
	v_mfma_f32_16x16x32_bf16 v[48:51], v[164:167], v[180:183], v[48:51]
	v_mfma_f32_16x16x32_bf16 v[40:43], v[172:175], v[180:183], v[40:43]
	v_mfma_f32_16x16x32_bf16 v[32:35], v[164:167], v[188:191], v[32:35]
	v_mfma_f32_16x16x32_bf16 v[24:27], v[172:175], v[188:191], v[24:27]
	v_mfma_f32_16x16x32_bf16 v[16:19], v[164:167], v[200:203], v[16:19]
	v_mfma_f32_16x16x32_bf16 v[8:11], v[172:175], v[200:203], v[8:11]
	v_mfma_f32_16x16x32_bf16 v[4:7], v[164:167], v[208:211], v[4:7]
	v_mfma_f32_16x16x32_bf16 v[0:3], v[172:175], v[208:211], v[0:3]
	v_mfma_f32_16x16x32_bf16 v[48:51], v[168:171], v[184:187], v[48:51]
	v_mfma_f32_16x16x32_bf16 v[40:43], v[176:179], v[184:187], v[40:43]
	v_mfma_f32_16x16x32_bf16 v[32:35], v[168:171], v[196:199], v[32:35]
	v_mfma_f32_16x16x32_bf16 v[24:27], v[176:179], v[196:199], v[24:27]
	v_mfma_f32_16x16x32_bf16 v[16:19], v[168:171], v[204:207], v[16:19]
	v_mfma_f32_16x16x32_bf16 v[8:11], v[176:179], v[204:207], v[8:11]
	v_mfma_f32_16x16x32_bf16 v[4:7], v[168:171], v[212:215], v[4:7]
	v_mfma_f32_16x16x32_bf16 v[0:3], v[176:179], v[212:215], v[0:3]
	s_setprio 0
	s_barrier
	s_add_i32 s52, s52, 2
	s_cmp_gt_u32 s52, 5
	s_mov_b64 s[20:21], s[22:23]
	s_cbranch_scc0 .LBB0_579
	s_and_b64 vcc, exec, s[12:13]
	s_cbranch_vccz .LBB0_582
	s_barrier

.LBB0_736:
	s_add_i32 s46, s38, 2
	s_add_u32 s36, s22, 0xfff80080
	s_addc_u32 s37, s23, -1
	s_add_i32 s47, 0, 0x10000
	s_cmp_eq_u32 s21, s38
	s_cselect_b32 s39, s17, s37
	s_cselect_b32 s38, s16, s36
	s_cselect_b32 s37, s19, s58
	s_cselect_b32 s36, s18, s57
	s_add_i32 s50, 0, 0x14000
	v_add_u32_e32 v142, s47, v234
	v_add_u32_e32 v158, s50, v234
	ds_read_b128 v[130:133], v142
	ds_read_b128 v[134:137], v142 offset:1024
	ds_read_b128 v[138:141], v142 offset:2048
	ds_read_b128 v[142:145], v142 offset:3072
	ds_read_b128 v[146:149], v158
	ds_read_b128 v[150:153], v158 offset:1024
	ds_read_b128 v[154:157], v158 offset:2048
	ds_read_b128 v[158:161], v158 offset:3072
	v_lshl_add_u64 v[196:197], s[22:23], 0, v[210:211]
	s_add_i32 m0, s29, 0xc000
	ds_read_b128 v[162:165], v236
	ds_read_b128 v[166:169], v236 offset:1024
	ds_read_b128 v[170:173], v236 offset:2048
	ds_read_b128 v[174:177], v236 offset:3072
	ds_read_b128 v[178:181], v236 offset:4096
	ds_read_b128 v[182:185], v236 offset:5120
	ds_read_b128 v[186:189], v236 offset:6144
	ds_read_b128 v[190:193], v236 offset:7168
	global_load_lds_dwordx4 v[196:197], off
	s_add_i32 m0, s29, 0xe000
	v_lshl_add_u64 v[196:197], s[22:23], 0, v[212:213]
	global_load_lds_dwordx4 v[196:197], off
	s_waitcnt vmcnt(8) lgkmcnt(0)
	s_barrier
	s_setprio 1
	v_mfma_f32_16x16x32_bf16 v[126:129], v[130:133], v[162:165], v[126:129]
	v_mfma_f32_16x16x32_bf16 v[122:125], v[138:141], v[162:165], v[122:125]
	v_mfma_f32_16x16x32_bf16 v[114:117], v[130:133], v[170:173], v[114:117]
	v_mfma_f32_16x16x32_bf16 v[106:109], v[138:141], v[170:173], v[106:109]
	v_mfma_f32_16x16x32_bf16 v[98:101], v[130:133], v[178:181], v[98:101]
	v_mfma_f32_16x16x32_bf16 v[88:91], v[138:141], v[178:181], v[88:91]
	v_mfma_f32_16x16x32_bf16 v[80:83], v[130:133], v[186:189], v[80:83]
	v_mfma_f32_16x16x32_bf16 v[72:75], v[138:141], v[186:189], v[72:75]
	v_mfma_f32_16x16x32_bf16 v[126:129], v[134:137], v[166:169], v[126:129]
	v_mfma_f32_16x16x32_bf16 v[122:125], v[142:145], v[166:169], v[122:125]
	v_mfma_f32_16x16x32_bf16 v[114:117], v[134:137], v[174:177], v[114:117]
	v_mfma_f32_16x16x32_bf16 v[106:109], v[142:145], v[174:177], v[106:109]
	v_mfma_f32_16x16x32_bf16 v[98:101], v[134:137], v[182:185], v[98:101]
	v_mfma_f32_16x16x32_bf16 v[88:91], v[142:145], v[182:185], v[88:91]
	v_mfma_f32_16x16x32_bf16 v[80:83], v[134:137], v[190:193], v[80:83]
	v_mfma_f32_16x16x32_bf16 v[72:75], v[142:145], v[190:193], v[72:75]
	v_mfma_f32_16x16x32_bf16 v[118:121], v[146:149], v[162:165], v[118:121]
	v_mfma_f32_16x16x32_bf16 v[110:113], v[154:157], v[162:165], v[110:113]
	v_mfma_f32_16x16x32_bf16 v[102:105], v[146:149], v[170:173], v[102:105]
	v_mfma_f32_16x16x32_bf16 v[92:95], v[154:157], v[170:173], v[92:95]
	v_mfma_f32_16x16x32_bf16 v[84:87], v[146:149], v[178:181], v[84:87]
	v_mfma_f32_16x16x32_bf16 v[76:79], v[154:157], v[178:181], v[76:79]
	v_mfma_f32_16x16x32_bf16 v[68:71], v[146:149], v[186:189], v[68:71]
	v_mfma_f32_16x16x32_bf16 v[64:67], v[154:157], v[186:189], v[64:67]
	v_mfma_f32_16x16x32_bf16 v[118:121], v[150:153], v[166:169], v[118:121]
	v_mfma_f32_16x16x32_bf16 v[110:113], v[158:161], v[166:169], v[110:113]
	v_mfma_f32_16x16x32_bf16 v[102:105], v[150:153], v[174:177], v[102:105]
	v_mfma_f32_16x16x32_bf16 v[92:95], v[158:161], v[174:177], v[92:95]
	v_mfma_f32_16x16x32_bf16 v[84:87], v[150:153], v[182:185], v[84:87]
	v_mfma_f32_16x16x32_bf16 v[76:79], v[158:161], v[182:185], v[76:79]
	v_mfma_f32_16x16x32_bf16 v[68:71], v[150:153], v[190:193], v[68:71]
	v_mfma_f32_16x16x32_bf16 v[64:67], v[158:161], v[190:193], v[64:67]
	s_setprio 0
	s_barrier
	s_add_i32 s47, s47, s0
	v_lshl_add_u64 v[196:197], s[36:37], 0, v[96:97]
	s_mov_b32 m0, s47
	ds_read_b128 v[162:165], v236 offset:16384
	ds_read_b128 v[166:169], v236 offset:17408
	ds_read_b128 v[170:173], v236 offset:18432
	ds_read_b128 v[174:177], v236 offset:19456
	ds_read_b128 v[178:181], v236 offset:20480
	ds_read_b128 v[182:185], v236 offset:21504
	ds_read_b128 v[186:189], v236 offset:22528
	ds_read_b128 v[190:193], v236 offset:23552
	global_load_lds_dwordx4 v[196:197], off
	s_add_i32 m0, s47, 0x2000
	s_add_u32 s62, s36, 0x80000
	v_lshl_add_u64 v[198:199], s[36:37], 0, v[208:209]
	s_addc_u32 s63, s37, 0
	s_add_i32 s47, s50, s0
	global_load_lds_dwordx4 v[198:199], off
	v_lshl_add_u64 v[200:201], s[62:63], 0, v[96:97]
	s_mov_b32 m0, s47
	v_lshl_add_u64 v[202:203], s[38:39], 0, v[206:207]
	global_load_lds_dwordx4 v[200:201], off
	s_add_i32 m0, s47, 0x2000
	v_lshl_add_u64 v[200:201], s[62:63], 0, v[208:209]
	global_load_lds_dwordx4 v[200:201], off
	s_mov_b32 m0, s29
	v_lshl_add_u64 v[200:201], s[38:39], 0, v[204:205]
	global_load_lds_dwordx4 v[200:201], off
	s_mov_b32 m0, s30
	s_nop 0
	global_load_lds_dwordx4 v[202:203], off
	s_waitcnt vmcnt(8) lgkmcnt(0)
	s_barrier
	s_setprio 1
	v_mfma_f32_16x16x32_bf16 v[60:63], v[130:133], v[162:165], v[60:63]
	v_mfma_f32_16x16x32_bf16 v[56:59], v[138:141], v[162:165], v[56:59]
	v_mfma_f32_16x16x32_bf16 v[48:51], v[130:133], v[170:173], v[48:51]
	v_mfma_f32_16x16x32_bf16 v[40:43], v[138:141], v[170:173], v[40:43]
	v_mfma_f32_16x16x32_bf16 v[32:35], v[130:133], v[178:181], v[32:35]
	v_mfma_f32_16x16x32_bf16 v[24:27], v[138:141], v[178:181], v[24:27]
	v_mfma_f32_16x16x32_bf16 v[16:19], v[130:133], v[186:189], v[16:19]
	v_mfma_f32_16x16x32_bf16 v[8:11], v[138:141], v[186:189], v[8:11]
	v_mfma_f32_16x16x32_bf16 v[60:63], v[134:137], v[166:169], v[60:63]
	v_mfma_f32_16x16x32_bf16 v[56:59], v[142:145], v[166:169], v[56:59]
	v_mfma_f32_16x16x32_bf16 v[48:51], v[134:137], v[174:177], v[48:51]
	v_mfma_f32_16x16x32_bf16 v[40:43], v[142:145], v[174:177], v[40:43]
	v_mfma_f32_16x16x32_bf16 v[32:35], v[134:137], v[182:185], v[32:35]
	v_mfma_f32_16x16x32_bf16 v[24:27], v[142:145], v[182:185], v[24:27]
	v_mfma_f32_16x16x32_bf16 v[16:19], v[134:137], v[190:193], v[16:19]
	v_mfma_f32_16x16x32_bf16 v[8:11], v[142:145], v[190:193], v[8:11]
	v_mfma_f32_16x16x32_bf16 v[52:55], v[146:149], v[162:165], v[52:55]
	v_mfma_f32_16x16x32_bf16 v[44:47], v[154:157], v[162:165], v[44:47]
	v_mfma_f32_16x16x32_bf16 v[36:39], v[146:149], v[170:173], v[36:39]
	v_mfma_f32_16x16x32_bf16 v[28:31], v[154:157], v[170:173], v[28:31]
	v_mfma_f32_16x16x32_bf16 v[20:23], v[146:149], v[178:181], v[20:23]
	v_mfma_f32_16x16x32_bf16 v[12:15], v[154:157], v[178:181], v[12:15]
	v_mfma_f32_16x16x32_bf16 v[4:7], v[146:149], v[186:189], v[4:7]
	v_mfma_f32_16x16x32_bf16 v[0:3], v[154:157], v[186:189], v[0:3]
	v_mfma_f32_16x16x32_bf16 v[52:55], v[150:153], v[166:169], v[52:55]
	v_mfma_f32_16x16x32_bf16 v[44:47], v[158:161], v[166:169], v[44:47]
	v_mfma_f32_16x16x32_bf16 v[36:39], v[150:153], v[174:177], v[36:39]
	v_mfma_f32_16x16x32_bf16 v[28:31], v[158:161], v[174:177], v[28:31]
	v_mfma_f32_16x16x32_bf16 v[20:23], v[150:153], v[182:185], v[20:23]
	v_mfma_f32_16x16x32_bf16 v[12:15], v[158:161], v[182:185], v[12:15]
	v_mfma_f32_16x16x32_bf16 v[4:7], v[150:153], v[190:193], v[4:7]
	v_mfma_f32_16x16x32_bf16 v[0:3], v[158:161], v[190:193], v[0:3]
	s_setprio 0
	s_barrier
	s_add_i32 s47, 0, 0x18000
	s_add_i32 s50, 0, 0x1c000
	v_add_u32_e32 v142, s47, v234
	v_add_u32_e32 v158, s50, v234
	ds_read_b128 v[130:133], v142
	ds_read_b128 v[134:137], v142 offset:1024
	ds_read_b128 v[138:141], v142 offset:2048
	ds_read_b128 v[142:145], v142 offset:3072
	ds_read_b128 v[146:149], v158
	ds_read_b128 v[150:153], v158 offset:1024
	ds_read_b128 v[154:157], v158 offset:2048
	ds_read_b128 v[158:161], v158 offset:3072
	s_add_u32 s38, s38, 0x80000
	s_addc_u32 s39, s39, 0
	s_mov_b32 m0, s31
	v_lshl_add_u64 v[214:215], s[38:39], 0, v[204:205]
	ds_read_b128 v[162:165], v236 offset:32768
	ds_read_b128 v[166:169], v236 offset:33792
	ds_read_b128 v[170:173], v236 offset:34816
	ds_read_b128 v[174:177], v236 offset:35840
	ds_read_b128 v[178:181], v236 offset:36864
	ds_read_b128 v[182:185], v236 offset:37888
	ds_read_b128 v[186:189], v236 offset:38912
	ds_read_b128 v[190:193], v236 offset:39936
	global_load_lds_dwordx4 v[214:215], off
	s_mov_b32 m0, s40
	v_lshl_add_u64 v[214:215], s[38:39], 0, v[206:207]
	global_load_lds_dwordx4 v[214:215], off
	s_waitcnt vmcnt(8) lgkmcnt(0)
	s_barrier
	s_setprio 1
	v_mfma_f32_16x16x32_bf16 v[126:129], v[130:133], v[162:165], v[126:129]
	v_mfma_f32_16x16x32_bf16 v[122:125], v[138:141], v[162:165], v[122:125]
	v_mfma_f32_16x16x32_bf16 v[114:117], v[130:133], v[170:173], v[114:117]
	v_mfma_f32_16x16x32_bf16 v[106:109], v[138:141], v[170:173], v[106:109]
	v_mfma_f32_16x16x32_bf16 v[98:101], v[130:133], v[178:181], v[98:101]
	v_mfma_f32_16x16x32_bf16 v[88:91], v[138:141], v[178:181], v[88:91]
	v_mfma_f32_16x16x32_bf16 v[80:83], v[130:133], v[186:189], v[80:83]
	v_mfma_f32_16x16x32_bf16 v[72:75], v[138:141], v[186:189], v[72:75]
	v_mfma_f32_16x16x32_bf16 v[126:129], v[134:137], v[166:169], v[126:129]
	v_mfma_f32_16x16x32_bf16 v[122:125], v[142:145], v[166:169], v[122:125]
	v_mfma_f32_16x16x32_bf16 v[114:117], v[134:137], v[174:177], v[114:117]
	v_mfma_f32_16x16x32_bf16 v[106:109], v[142:145], v[174:177], v[106:109]
	v_mfma_f32_16x16x32_bf16 v[98:101], v[134:137], v[182:185], v[98:101]
	v_mfma_f32_16x16x32_bf16 v[88:91], v[142:145], v[182:185], v[88:91]
	v_mfma_f32_16x16x32_bf16 v[80:83], v[134:137], v[190:193], v[80:83]
	v_mfma_f32_16x16x32_bf16 v[72:75], v[142:145], v[190:193], v[72:75]
	v_mfma_f32_16x16x32_bf16 v[118:121], v[146:149], v[162:165], v[118:121]
	v_mfma_f32_16x16x32_bf16 v[110:113], v[154:157], v[162:165], v[110:113]
	v_mfma_f32_16x16x32_bf16 v[102:105], v[146:149], v[170:173], v[102:105]
	v_mfma_f32_16x16x32_bf16 v[92:95], v[154:157], v[170:173], v[92:95]
	v_mfma_f32_16x16x32_bf16 v[84:87], v[146:149], v[178:181], v[84:87]
	v_mfma_f32_16x16x32_bf16 v[76:79], v[154:157], v[178:181], v[76:79]
	v_mfma_f32_16x16x32_bf16 v[68:71], v[146:149], v[186:189], v[68:71]
	v_mfma_f32_16x16x32_bf16 v[64:67], v[154:157], v[186:189], v[64:67]
	v_mfma_f32_16x16x32_bf16 v[118:121], v[150:153], v[166:169], v[118:121]
	v_mfma_f32_16x16x32_bf16 v[110:113], v[158:161], v[166:169], v[110:113]
	v_mfma_f32_16x16x32_bf16 v[102:105], v[150:153], v[174:177], v[102:105]
	v_mfma_f32_16x16x32_bf16 v[92:95], v[158:161], v[174:177], v[92:95]
	v_mfma_f32_16x16x32_bf16 v[84:87], v[150:153], v[182:185], v[84:87]
	v_mfma_f32_16x16x32_bf16 v[76:79], v[158:161], v[182:185], v[76:79]
	v_mfma_f32_16x16x32_bf16 v[68:71], v[150:153], v[190:193], v[68:71]
	v_mfma_f32_16x16x32_bf16 v[64:67], v[158:161], v[190:193], v[64:67]
	s_setprio 0
	s_barrier
	s_add_i32 s38, s47, s0
	v_lshl_add_u64 v[196:197], v[196:197], 0, s[82:83]
	s_mov_b32 m0, s38
	ds_read_b128 v[162:165], v236 offset:49152
	ds_read_b128 v[166:169], v236 offset:50176
	ds_read_b128 v[170:173], v236 offset:51200
	ds_read_b128 v[174:177], v236 offset:52224
	ds_read_b128 v[178:181], v236 offset:53248
	ds_read_b128 v[182:185], v236 offset:54272
	ds_read_b128 v[186:189], v236 offset:55296
	ds_read_b128 v[190:193], v236 offset:56320
	global_load_lds_dwordx4 v[196:197], off
	s_add_i32 m0, s38, 0x2000
	s_add_u32 s36, s36, 0x80080
	v_lshl_add_u64 v[196:197], v[198:199], 0, s[82:83]
	s_addc_u32 s37, s37, 0
	s_add_i32 s38, s50, s0
	global_load_lds_dwordx4 v[196:197], off
	s_mov_b32 m0, s38
	v_lshl_add_u64 v[196:197], s[36:37], 0, v[96:97]
	global_load_lds_dwordx4 v[196:197], off
	s_add_i32 m0, s38, 0x2000
	v_lshl_add_u64 v[196:197], s[36:37], 0, v[208:209]
	global_load_lds_dwordx4 v[196:197], off
	s_mov_b32 m0, s45
	v_lshl_add_u64 v[196:197], v[200:201], 0, s[82:83]
	global_load_lds_dwordx4 v[196:197], off
	s_mov_b32 m0, s48
	v_lshl_add_u64 v[196:197], v[202:203], 0, s[82:83]
	global_load_lds_dwordx4 v[196:197], off
	s_waitcnt vmcnt(8) lgkmcnt(0)
	s_barrier
	s_setprio 1
	v_mfma_f32_16x16x32_bf16 v[60:63], v[130:133], v[162:165], v[60:63]
	v_mfma_f32_16x16x32_bf16 v[56:59], v[138:141], v[162:165], v[56:59]
	v_mfma_f32_16x16x32_bf16 v[48:51], v[130:133], v[170:173], v[48:51]
	v_mfma_f32_16x16x32_bf16 v[40:43], v[138:141], v[170:173], v[40:43]
	v_mfma_f32_16x16x32_bf16 v[32:35], v[130:133], v[178:181], v[32:35]
	v_mfma_f32_16x16x32_bf16 v[24:27], v[138:141], v[178:181], v[24:27]
	v_mfma_f32_16x16x32_bf16 v[16:19], v[130:133], v[186:189], v[16:19]
	v_mfma_f32_16x16x32_bf16 v[8:11], v[138:141], v[186:189], v[8:11]
	v_mfma_f32_16x16x32_bf16 v[60:63], v[134:137], v[166:169], v[60:63]
	v_mfma_f32_16x16x32_bf16 v[56:59], v[142:145], v[166:169], v[56:59]
	v_mfma_f32_16x16x32_bf16 v[48:51], v[134:137], v[174:177], v[48:51]
	v_mfma_f32_16x16x32_bf16 v[40:43], v[142:145], v[174:177], v[40:43]
	v_mfma_f32_16x16x32_bf16 v[32:35], v[134:137], v[182:185], v[32:35]
	v_mfma_f32_16x16x32_bf16 v[24:27], v[142:145], v[182:185], v[24:27]
	v_mfma_f32_16x16x32_bf16 v[16:19], v[134:137], v[190:193], v[16:19]
	v_mfma_f32_16x16x32_bf16 v[8:11], v[142:145], v[190:193], v[8:11]
	v_mfma_f32_16x16x32_bf16 v[52:55], v[146:149], v[162:165], v[52:55]
	v_mfma_f32_16x16x32_bf16 v[44:47], v[154:157], v[162:165], v[44:47]
	v_mfma_f32_16x16x32_bf16 v[36:39], v[146:149], v[170:173], v[36:39]
	v_mfma_f32_16x16x32_bf16 v[28:31], v[154:157], v[170:173], v[28:31]
	v_mfma_f32_16x16x32_bf16 v[20:23], v[146:149], v[178:181], v[20:23]
	v_mfma_f32_16x16x32_bf16 v[12:15], v[154:157], v[178:181], v[12:15]
	v_mfma_f32_16x16x32_bf16 v[4:7], v[146:149], v[186:189], v[4:7]
	v_mfma_f32_16x16x32_bf16 v[0:3], v[154:157], v[186:189], v[0:3]
	v_mfma_f32_16x16x32_bf16 v[52:55], v[150:153], v[166:169], v[52:55]
	v_mfma_f32_16x16x32_bf16 v[44:47], v[158:161], v[166:169], v[44:47]
	v_mfma_f32_16x16x32_bf16 v[36:39], v[150:153], v[174:177], v[36:39]
	v_mfma_f32_16x16x32_bf16 v[28:31], v[158:161], v[174:177], v[28:31]
	v_mfma_f32_16x16x32_bf16 v[20:23], v[150:153], v[182:185], v[20:23]
	v_mfma_f32_16x16x32_bf16 v[12:15], v[158:161], v[182:185], v[12:15]
	v_mfma_f32_16x16x32_bf16 v[4:7], v[150:153], v[190:193], v[4:7]
	v_mfma_f32_16x16x32_bf16 v[0:3], v[158:161], v[190:193], v[0:3]
	s_setprio 0
	s_barrier
	s_add_u32 s22, s22, 0x100
	s_addc_u32 s23, s23, 0
	s_add_u32 s57, s57, 0x100
	s_addc_u32 s58, s58, 0
	s_cmp_ge_i32 s46, s15
	s_mov_b32 s38, s46
	s_cbranch_scc0 .LBB0_736
	s_and_b64 vcc, exec, s[10:11]
	s_cbranch_vccz .LBB0_739
	s_barrier

.LBB0_890:
	s_add_i32 s46, s40, 2
	s_add_u32 s38, s36, 0xfff80080
	s_addc_u32 s39, s37, -1
	s_add_i32 s47, 0, 0x10000
	s_cmp_eq_u32 s42, s40
	s_cselect_b32 s41, s21, s39
	s_cselect_b32 s40, s20, s38
	v_add_u32_e32 v142, s47, v145
	s_cselect_b32 s39, s23, s56
	s_cselect_b32 s38, s22, s43
	s_add_i32 s50, 0, 0x14000
	ds_read_b128 v[148:151], v142
	ds_read_b128 v[152:155], v142 offset:1024
	ds_read_b128 v[156:159], v142 offset:2048
	ds_read_b128 v[160:163], v142 offset:3072
	v_add_u32_e32 v142, s50, v145
	ds_read_b128 v[164:167], v142
	ds_read_b128 v[168:171], v142 offset:1024
	ds_read_b128 v[172:175], v142 offset:2048
	ds_read_b128 v[176:179], v142 offset:3072
	v_lshl_add_u64 v[142:143], s[36:37], 0, v[138:139]
	s_add_i32 m0, s30, 0xc000
	ds_read_b128 v[180:183], v146
	ds_read_b128 v[184:187], v146 offset:1024
	ds_read_b128 v[188:191], v146 offset:2048
	ds_read_b128 v[196:199], v146 offset:3072
	ds_read_b128 v[200:203], v146 offset:4096
	ds_read_b128 v[204:207], v146 offset:5120
	ds_read_b128 v[208:211], v146 offset:6144
	ds_read_b128 v[212:215], v146 offset:7168
	global_load_lds_dwordx4 v[142:143], off
	s_add_i32 m0, s30, 0xe000
	v_lshl_add_u64 v[142:143], s[36:37], 0, v[140:141]
	global_load_lds_dwordx4 v[142:143], off
	s_waitcnt vmcnt(8) lgkmcnt(0)
	s_barrier
	s_setprio 1
	v_mfma_f32_16x16x32_bf16 v[126:129], v[148:151], v[180:183], v[126:129]
	v_mfma_f32_16x16x32_bf16 v[122:125], v[156:159], v[180:183], v[122:125]
	v_mfma_f32_16x16x32_bf16 v[118:121], v[148:151], v[188:191], v[118:121]
	v_mfma_f32_16x16x32_bf16 v[110:113], v[156:159], v[188:191], v[110:113]
	v_mfma_f32_16x16x32_bf16 v[102:105], v[148:151], v[200:203], v[102:105]
	v_mfma_f32_16x16x32_bf16 v[92:95], v[156:159], v[200:203], v[92:95]
	v_mfma_f32_16x16x32_bf16 v[84:87], v[148:151], v[208:211], v[84:87]
	v_mfma_f32_16x16x32_bf16 v[76:79], v[156:159], v[208:211], v[76:79]
	v_mfma_f32_16x16x32_bf16 v[126:129], v[152:155], v[184:187], v[126:129]
	v_mfma_f32_16x16x32_bf16 v[122:125], v[160:163], v[184:187], v[122:125]
	v_mfma_f32_16x16x32_bf16 v[118:121], v[152:155], v[196:199], v[118:121]
	v_mfma_f32_16x16x32_bf16 v[110:113], v[160:163], v[196:199], v[110:113]
	v_mfma_f32_16x16x32_bf16 v[102:105], v[152:155], v[204:207], v[102:105]
	v_mfma_f32_16x16x32_bf16 v[92:95], v[160:163], v[204:207], v[92:95]
	v_mfma_f32_16x16x32_bf16 v[84:87], v[152:155], v[212:215], v[84:87]
	v_mfma_f32_16x16x32_bf16 v[76:79], v[160:163], v[212:215], v[76:79]
	v_mfma_f32_16x16x32_bf16 v[114:117], v[164:167], v[180:183], v[114:117]
	v_mfma_f32_16x16x32_bf16 v[106:109], v[172:175], v[180:183], v[106:109]
	v_mfma_f32_16x16x32_bf16 v[98:101], v[164:167], v[188:191], v[98:101]
	v_mfma_f32_16x16x32_bf16 v[88:91], v[172:175], v[188:191], v[88:91]
	v_mfma_f32_16x16x32_bf16 v[80:83], v[164:167], v[200:203], v[80:83]
	v_mfma_f32_16x16x32_bf16 v[72:75], v[172:175], v[200:203], v[72:75]
	v_mfma_f32_16x16x32_bf16 v[68:71], v[164:167], v[208:211], v[68:71]
	v_mfma_f32_16x16x32_bf16 v[64:67], v[172:175], v[208:211], v[64:67]
	v_mfma_f32_16x16x32_bf16 v[114:117], v[168:171], v[184:187], v[114:117]
	v_mfma_f32_16x16x32_bf16 v[106:109], v[176:179], v[184:187], v[106:109]
	v_mfma_f32_16x16x32_bf16 v[98:101], v[168:171], v[196:199], v[98:101]
	v_mfma_f32_16x16x32_bf16 v[88:91], v[176:179], v[196:199], v[88:91]
	v_mfma_f32_16x16x32_bf16 v[80:83], v[168:171], v[204:207], v[80:83]
	v_mfma_f32_16x16x32_bf16 v[72:75], v[176:179], v[204:207], v[72:75]
	v_mfma_f32_16x16x32_bf16 v[68:71], v[168:171], v[212:215], v[68:71]
	v_mfma_f32_16x16x32_bf16 v[64:67], v[176:179], v[212:215], v[64:67]
	s_setprio 0
	s_barrier
	s_add_i32 s47, s47, s15
	v_lshl_add_u64 v[142:143], s[38:39], 0, v[132:133]
	s_mov_b32 m0, s47
	ds_read_b128 v[180:183], v146 offset:16384
	ds_read_b128 v[184:187], v146 offset:17408
	ds_read_b128 v[188:191], v146 offset:18432
	ds_read_b128 v[196:199], v146 offset:19456
	ds_read_b128 v[200:203], v146 offset:20480
	ds_read_b128 v[204:207], v146 offset:21504
	ds_read_b128 v[208:211], v146 offset:22528
	ds_read_b128 v[212:215], v146 offset:23552
	global_load_lds_dwordx4 v[142:143], off
	s_add_i32 m0, s47, 0x2000
	s_add_u32 s58, s38, 0x80000
	v_lshl_add_u64 v[192:193], s[38:39], 0, v[136:137]
	s_addc_u32 s59, s39, 0
	s_add_i32 s47, s50, s15
	global_load_lds_dwordx4 v[192:193], off
	v_lshl_add_u64 v[216:217], s[58:59], 0, v[132:133]
	s_mov_b32 m0, s47
	v_lshl_add_u64 v[218:219], s[40:41], 0, v[134:135]
	global_load_lds_dwordx4 v[216:217], off
	s_add_i32 m0, s47, 0x2000
	v_lshl_add_u64 v[216:217], s[58:59], 0, v[136:137]
	global_load_lds_dwordx4 v[216:217], off
	s_mov_b32 m0, s30
	v_lshl_add_u64 v[216:217], s[40:41], 0, v[130:131]
	global_load_lds_dwordx4 v[216:217], off
	s_mov_b32 m0, s31
	s_nop 0
	global_load_lds_dwordx4 v[218:219], off
	s_waitcnt vmcnt(8) lgkmcnt(0)
	s_barrier
	s_setprio 1
	v_mfma_f32_16x16x32_bf16 v[60:63], v[148:151], v[180:183], v[60:63]
	v_mfma_f32_16x16x32_bf16 v[56:59], v[156:159], v[180:183], v[56:59]
	v_mfma_f32_16x16x32_bf16 v[52:55], v[148:151], v[188:191], v[52:55]
	v_mfma_f32_16x16x32_bf16 v[44:47], v[156:159], v[188:191], v[44:47]
	v_mfma_f32_16x16x32_bf16 v[36:39], v[148:151], v[200:203], v[36:39]
	v_mfma_f32_16x16x32_bf16 v[28:31], v[156:159], v[200:203], v[28:31]
	v_mfma_f32_16x16x32_bf16 v[20:23], v[148:151], v[208:211], v[20:23]
	v_mfma_f32_16x16x32_bf16 v[12:15], v[156:159], v[208:211], v[12:15]
	v_mfma_f32_16x16x32_bf16 v[60:63], v[152:155], v[184:187], v[60:63]
	v_mfma_f32_16x16x32_bf16 v[56:59], v[160:163], v[184:187], v[56:59]
	v_mfma_f32_16x16x32_bf16 v[52:55], v[152:155], v[196:199], v[52:55]
	v_mfma_f32_16x16x32_bf16 v[44:47], v[160:163], v[196:199], v[44:47]
	v_mfma_f32_16x16x32_bf16 v[36:39], v[152:155], v[204:207], v[36:39]
	v_mfma_f32_16x16x32_bf16 v[28:31], v[160:163], v[204:207], v[28:31]
	v_mfma_f32_16x16x32_bf16 v[20:23], v[152:155], v[212:215], v[20:23]
	v_mfma_f32_16x16x32_bf16 v[12:15], v[160:163], v[212:215], v[12:15]
	v_mfma_f32_16x16x32_bf16 v[48:51], v[164:167], v[180:183], v[48:51]
	v_mfma_f32_16x16x32_bf16 v[40:43], v[172:175], v[180:183], v[40:43]
	v_mfma_f32_16x16x32_bf16 v[32:35], v[164:167], v[188:191], v[32:35]
	v_mfma_f32_16x16x32_bf16 v[24:27], v[172:175], v[188:191], v[24:27]
	v_mfma_f32_16x16x32_bf16 v[16:19], v[164:167], v[200:203], v[16:19]
	v_mfma_f32_16x16x32_bf16 v[8:11], v[172:175], v[200:203], v[8:11]
	v_mfma_f32_16x16x32_bf16 v[4:7], v[164:167], v[208:211], v[4:7]
	v_mfma_f32_16x16x32_bf16 v[0:3], v[172:175], v[208:211], v[0:3]
	v_mfma_f32_16x16x32_bf16 v[48:51], v[168:171], v[184:187], v[48:51]
	v_mfma_f32_16x16x32_bf16 v[40:43], v[176:179], v[184:187], v[40:43]
	v_mfma_f32_16x16x32_bf16 v[32:35], v[168:171], v[196:199], v[32:35]
	v_mfma_f32_16x16x32_bf16 v[24:27], v[176:179], v[196:199], v[24:27]
	v_mfma_f32_16x16x32_bf16 v[16:19], v[168:171], v[204:207], v[16:19]
	v_mfma_f32_16x16x32_bf16 v[8:11], v[176:179], v[204:207], v[8:11]
	v_mfma_f32_16x16x32_bf16 v[4:7], v[168:171], v[212:215], v[4:7]
	v_mfma_f32_16x16x32_bf16 v[0:3], v[176:179], v[212:215], v[0:3]
	s_setprio 0
	s_barrier
	s_add_i32 s47, 0, 0x18000
	v_add_u32_e32 v147, s47, v145
	s_add_i32 s50, 0, 0x1c000
	ds_read_b128 v[148:151], v147
	ds_read_b128 v[152:155], v147 offset:1024
	ds_read_b128 v[156:159], v147 offset:2048
	ds_read_b128 v[160:163], v147 offset:3072
	v_add_u32_e32 v147, s50, v145
	ds_read_b128 v[164:167], v147
	ds_read_b128 v[168:171], v147 offset:1024
	ds_read_b128 v[172:175], v147 offset:2048
	ds_read_b128 v[176:179], v147 offset:3072
	s_add_u32 s40, s40, 0x80000
	s_addc_u32 s41, s41, 0
	s_mov_b32 m0, s44
	v_lshl_add_u64 v[220:221], s[40:41], 0, v[130:131]
	ds_read_b128 v[180:183], v146 offset:32768
	ds_read_b128 v[184:187], v146 offset:33792
	ds_read_b128 v[188:191], v146 offset:34816
	ds_read_b128 v[196:199], v146 offset:35840
	ds_read_b128 v[200:203], v146 offset:36864
	ds_read_b128 v[204:207], v146 offset:37888
	ds_read_b128 v[208:211], v146 offset:38912
	ds_read_b128 v[212:215], v146 offset:39936
	global_load_lds_dwordx4 v[220:221], off
	s_mov_b32 m0, s45
	v_lshl_add_u64 v[220:221], s[40:41], 0, v[134:135]
	global_load_lds_dwordx4 v[220:221], off
	s_waitcnt vmcnt(8) lgkmcnt(0)
	s_barrier
	s_setprio 1
	v_mfma_f32_16x16x32_bf16 v[126:129], v[148:151], v[180:183], v[126:129]
	v_mfma_f32_16x16x32_bf16 v[122:125], v[156:159], v[180:183], v[122:125]
	v_mfma_f32_16x16x32_bf16 v[118:121], v[148:151], v[188:191], v[118:121]
	v_mfma_f32_16x16x32_bf16 v[110:113], v[156:159], v[188:191], v[110:113]
	v_mfma_f32_16x16x32_bf16 v[102:105], v[148:151], v[200:203], v[102:105]
	v_mfma_f32_16x16x32_bf16 v[92:95], v[156:159], v[200:203], v[92:95]
	v_mfma_f32_16x16x32_bf16 v[84:87], v[148:151], v[208:211], v[84:87]
	v_mfma_f32_16x16x32_bf16 v[76:79], v[156:159], v[208:211], v[76:79]
	v_mfma_f32_16x16x32_bf16 v[126:129], v[152:155], v[184:187], v[126:129]
	v_mfma_f32_16x16x32_bf16 v[122:125], v[160:163], v[184:187], v[122:125]
	v_mfma_f32_16x16x32_bf16 v[118:121], v[152:155], v[196:199], v[118:121]
	v_mfma_f32_16x16x32_bf16 v[110:113], v[160:163], v[196:199], v[110:113]
	v_mfma_f32_16x16x32_bf16 v[102:105], v[152:155], v[204:207], v[102:105]
	v_mfma_f32_16x16x32_bf16 v[92:95], v[160:163], v[204:207], v[92:95]
	v_mfma_f32_16x16x32_bf16 v[84:87], v[152:155], v[212:215], v[84:87]
	v_mfma_f32_16x16x32_bf16 v[76:79], v[160:163], v[212:215], v[76:79]
	v_mfma_f32_16x16x32_bf16 v[114:117], v[164:167], v[180:183], v[114:117]
	v_mfma_f32_16x16x32_bf16 v[106:109], v[172:175], v[180:183], v[106:109]
	v_mfma_f32_16x16x32_bf16 v[98:101], v[164:167], v[188:191], v[98:101]
	v_mfma_f32_16x16x32_bf16 v[88:91], v[172:175], v[188:191], v[88:91]
	v_mfma_f32_16x16x32_bf16 v[80:83], v[164:167], v[200:203], v[80:83]
	v_mfma_f32_16x16x32_bf16 v[72:75], v[172:175], v[200:203], v[72:75]
	v_mfma_f32_16x16x32_bf16 v[68:71], v[164:167], v[208:211], v[68:71]
	v_mfma_f32_16x16x32_bf16 v[64:67], v[172:175], v[208:211], v[64:67]
	v_mfma_f32_16x16x32_bf16 v[114:117], v[168:171], v[184:187], v[114:117]
	v_mfma_f32_16x16x32_bf16 v[106:109], v[176:179], v[184:187], v[106:109]
	v_mfma_f32_16x16x32_bf16 v[98:101], v[168:171], v[196:199], v[98:101]
	v_mfma_f32_16x16x32_bf16 v[88:91], v[176:179], v[196:199], v[88:91]
	v_mfma_f32_16x16x32_bf16 v[80:83], v[168:171], v[204:207], v[80:83]
	v_mfma_f32_16x16x32_bf16 v[72:75], v[176:179], v[204:207], v[72:75]
	v_mfma_f32_16x16x32_bf16 v[68:71], v[168:171], v[212:215], v[68:71]
	v_mfma_f32_16x16x32_bf16 v[64:67], v[176:179], v[212:215], v[64:67]
	s_setprio 0
	s_barrier
	s_add_i32 s40, s47, s15
	v_lshl_add_u64 v[142:143], v[142:143], 0, s[82:83]
	s_mov_b32 m0, s40
	ds_read_b128 v[180:183], v146 offset:49152
	ds_read_b128 v[184:187], v146 offset:50176
	ds_read_b128 v[188:191], v146 offset:51200
	ds_read_b128 v[196:199], v146 offset:52224
	ds_read_b128 v[200:203], v146 offset:53248
	ds_read_b128 v[204:207], v146 offset:54272
	ds_read_b128 v[208:211], v146 offset:55296
	ds_read_b128 v[212:215], v146 offset:56320
	global_load_lds_dwordx4 v[142:143], off
	s_add_i32 m0, s40, 0x2000
	s_add_u32 s38, s38, 0x80080
	v_lshl_add_u64 v[142:143], v[192:193], 0, s[82:83]
	s_addc_u32 s39, s39, 0
	s_add_i32 s40, s50, s15
	global_load_lds_dwordx4 v[142:143], off
	s_mov_b32 m0, s40
	v_lshl_add_u64 v[142:143], s[38:39], 0, v[132:133]
	global_load_lds_dwordx4 v[142:143], off
	s_add_i32 m0, s40, 0x2000
	v_lshl_add_u64 v[142:143], s[38:39], 0, v[136:137]
	global_load_lds_dwordx4 v[142:143], off
	s_mov_b32 m0, s48
	v_lshl_add_u64 v[142:143], v[216:217], 0, s[82:83]
	global_load_lds_dwordx4 v[142:143], off
	s_mov_b32 m0, s49
	v_lshl_add_u64 v[142:143], v[218:219], 0, s[82:83]
	global_load_lds_dwordx4 v[142:143], off
	s_waitcnt vmcnt(8) lgkmcnt(0)
	s_barrier
	s_setprio 1
	v_mfma_f32_16x16x32_bf16 v[60:63], v[148:151], v[180:183], v[60:63]
	v_mfma_f32_16x16x32_bf16 v[56:59], v[156:159], v[180:183], v[56:59]
	v_mfma_f32_16x16x32_bf16 v[52:55], v[148:151], v[188:191], v[52:55]
	v_mfma_f32_16x16x32_bf16 v[44:47], v[156:159], v[188:191], v[44:47]
	v_mfma_f32_16x16x32_bf16 v[36:39], v[148:151], v[200:203], v[36:39]
	v_mfma_f32_16x16x32_bf16 v[28:31], v[156:159], v[200:203], v[28:31]
	v_mfma_f32_16x16x32_bf16 v[20:23], v[148:151], v[208:211], v[20:23]
	v_mfma_f32_16x16x32_bf16 v[12:15], v[156:159], v[208:211], v[12:15]
	v_mfma_f32_16x16x32_bf16 v[60:63], v[152:155], v[184:187], v[60:63]
	v_mfma_f32_16x16x32_bf16 v[56:59], v[160:163], v[184:187], v[56:59]
	v_mfma_f32_16x16x32_bf16 v[52:55], v[152:155], v[196:199], v[52:55]
	v_mfma_f32_16x16x32_bf16 v[44:47], v[160:163], v[196:199], v[44:47]
	v_mfma_f32_16x16x32_bf16 v[36:39], v[152:155], v[204:207], v[36:39]
	v_mfma_f32_16x16x32_bf16 v[28:31], v[160:163], v[204:207], v[28:31]
	v_mfma_f32_16x16x32_bf16 v[20:23], v[152:155], v[212:215], v[20:23]
	v_mfma_f32_16x16x32_bf16 v[12:15], v[160:163], v[212:215], v[12:15]
	v_mfma_f32_16x16x32_bf16 v[48:51], v[164:167], v[180:183], v[48:51]
	v_mfma_f32_16x16x32_bf16 v[40:43], v[172:175], v[180:183], v[40:43]
	v_mfma_f32_16x16x32_bf16 v[32:35], v[164:167], v[188:191], v[32:35]
	v_mfma_f32_16x16x32_bf16 v[24:27], v[172:175], v[188:191], v[24:27]
	v_mfma_f32_16x16x32_bf16 v[16:19], v[164:167], v[200:203], v[16:19]
	v_mfma_f32_16x16x32_bf16 v[8:11], v[172:175], v[200:203], v[8:11]
	v_mfma_f32_16x16x32_bf16 v[4:7], v[164:167], v[208:211], v[4:7]
	v_mfma_f32_16x16x32_bf16 v[0:3], v[172:175], v[208:211], v[0:3]
	v_mfma_f32_16x16x32_bf16 v[48:51], v[168:171], v[184:187], v[48:51]
	v_mfma_f32_16x16x32_bf16 v[40:43], v[176:179], v[184:187], v[40:43]
	v_mfma_f32_16x16x32_bf16 v[32:35], v[168:171], v[196:199], v[32:35]
	v_mfma_f32_16x16x32_bf16 v[24:27], v[176:179], v[196:199], v[24:27]
	v_mfma_f32_16x16x32_bf16 v[16:19], v[168:171], v[204:207], v[16:19]
	v_mfma_f32_16x16x32_bf16 v[8:11], v[176:179], v[204:207], v[8:11]
	v_mfma_f32_16x16x32_bf16 v[4:7], v[168:171], v[212:215], v[4:7]
	v_mfma_f32_16x16x32_bf16 v[0:3], v[176:179], v[212:215], v[0:3]
	s_setprio 0
	s_barrier
	s_add_u32 s36, s36, 0x100
	s_addc_u32 s37, s37, 0
	s_add_u32 s43, s43, 0x100
	s_addc_u32 s56, s56, 0
	s_cmp_ge_i32 s46, s19
	s_mov_b32 s40, s46
	s_cbranch_scc0 .LBB0_890
	s_and_b64 vcc, exec, s[10:11]
	s_cbranch_vccz .LBB0_893
	s_barrier

.LBB0_1145:
	s_add_i32 s46, s44, 2
	s_add_u32 s42, s40, 0xfff80080
	s_addc_u32 s43, s41, -1
	s_add_i32 s47, 0, 0x10000
	s_cmp_eq_u32 s67, s44
	s_cselect_b32 s45, s81, s43
	s_cselect_b32 s44, s80, s42
	s_cselect_b32 s43, s53, vcc_lo
	s_cselect_b32 s42, s52, s92
	s_add_i32 vcc_hi, 0, 0x14000
	v_add_u32_e32 v110, s47, v204
	v_add_u32_e32 v126, vcc_hi, v204
	ds_read_b128 v[80:83], v110
	ds_read_b128 v[102:105], v110 offset:1024
	ds_read_b128 v[106:109], v110 offset:2048
	ds_read_b128 v[110:113], v110 offset:3072
	ds_read_b128 v[114:117], v126
	ds_read_b128 v[118:121], v126 offset:1024
	ds_read_b128 v[122:125], v126 offset:2048
	ds_read_b128 v[126:129], v126 offset:3072
	v_lshl_add_u64 v[190:191], s[40:41], 0, v[170:171]
	s_add_i32 m0, s88, 0xc000
	ds_read_b128 v[174:177], v207
	ds_read_b128 v[178:181], v207 offset:1024
	ds_read_b128 v[182:185], v207 offset:2048
	ds_read_b128 v[186:189], v207 offset:3072
	ds_read_b128 v[196:199], v207 offset:4096
	ds_read_b128 v[200:203], v207 offset:5120
	ds_read_b128 v[208:211], v207 offset:6144
	ds_read_b128 v[212:215], v207 offset:7168
	global_load_lds_dwordx4 v[190:191], off
	s_add_i32 m0, s88, 0xe000
	v_lshl_add_u64 v[190:191], s[40:41], 0, v[172:173]
	global_load_lds_dwordx4 v[190:191], off
	s_waitcnt vmcnt(8) lgkmcnt(0)
	s_barrier
	s_setprio 1
	v_mfma_f32_16x16x32_bf16 v[98:101], v[80:83], v[174:177], v[98:101]
	v_mfma_f32_16x16x32_bf16 v[88:91], v[106:109], v[174:177], v[88:91]
	v_mfma_f32_16x16x32_bf16 v[158:161], v[80:83], v[182:185], v[158:161]
	v_mfma_f32_16x16x32_bf16 v[154:157], v[106:109], v[182:185], v[154:157]
	v_mfma_f32_16x16x32_bf16 v[146:149], v[80:83], v[196:199], v[146:149]
	v_mfma_f32_16x16x32_bf16 v[138:141], v[106:109], v[196:199], v[138:141]
	v_mfma_f32_16x16x32_bf16 v[76:79], v[80:83], v[208:211], v[76:79]
	v_mfma_f32_16x16x32_bf16 v[68:71], v[106:109], v[208:211], v[68:71]
	v_mfma_f32_16x16x32_bf16 v[98:101], v[102:105], v[178:181], v[98:101]
	v_mfma_f32_16x16x32_bf16 v[88:91], v[110:113], v[178:181], v[88:91]
	v_mfma_f32_16x16x32_bf16 v[158:161], v[102:105], v[186:189], v[158:161]
	v_mfma_f32_16x16x32_bf16 v[154:157], v[110:113], v[186:189], v[154:157]
	v_mfma_f32_16x16x32_bf16 v[146:149], v[102:105], v[200:203], v[146:149]
	v_mfma_f32_16x16x32_bf16 v[138:141], v[110:113], v[200:203], v[138:141]
	v_mfma_f32_16x16x32_bf16 v[76:79], v[102:105], v[212:215], v[76:79]
	v_mfma_f32_16x16x32_bf16 v[68:71], v[110:113], v[212:215], v[68:71]
	v_mfma_f32_16x16x32_bf16 v[92:95], v[114:117], v[174:177], v[92:95]
	v_mfma_f32_16x16x32_bf16 v[84:87], v[122:125], v[174:177], v[84:87]
	v_mfma_f32_16x16x32_bf16 v[150:153], v[114:117], v[182:185], v[150:153]
	v_mfma_f32_16x16x32_bf16 v[142:145], v[122:125], v[182:185], v[142:145]
	v_mfma_f32_16x16x32_bf16 v[134:137], v[114:117], v[196:199], v[134:137]
	v_mfma_f32_16x16x32_bf16 v[130:133], v[122:125], v[196:199], v[130:133]
	v_mfma_f32_16x16x32_bf16 v[72:75], v[114:117], v[208:211], v[72:75]
	v_mfma_f32_16x16x32_bf16 v[64:67], v[122:125], v[208:211], v[64:67]
	v_mfma_f32_16x16x32_bf16 v[92:95], v[118:121], v[178:181], v[92:95]
	v_mfma_f32_16x16x32_bf16 v[84:87], v[126:129], v[178:181], v[84:87]
	v_mfma_f32_16x16x32_bf16 v[150:153], v[118:121], v[186:189], v[150:153]
	v_mfma_f32_16x16x32_bf16 v[142:145], v[126:129], v[186:189], v[142:145]
	v_mfma_f32_16x16x32_bf16 v[134:137], v[118:121], v[200:203], v[134:137]
	v_mfma_f32_16x16x32_bf16 v[130:133], v[126:129], v[200:203], v[130:133]
	v_mfma_f32_16x16x32_bf16 v[72:75], v[118:121], v[212:215], v[72:75]
	v_mfma_f32_16x16x32_bf16 v[64:67], v[126:129], v[212:215], v[64:67]
	s_setprio 0
	s_barrier
	s_add_i32 s47, s47, s59
	v_lshl_add_u64 v[190:191], s[42:43], 0, v[96:97]
	s_mov_b32 m0, s47
	ds_read_b128 v[174:177], v207 offset:16384
	ds_read_b128 v[178:181], v207 offset:17408
	ds_read_b128 v[182:185], v207 offset:18432
	ds_read_b128 v[186:189], v207 offset:19456
	ds_read_b128 v[196:199], v207 offset:20480
	ds_read_b128 v[200:203], v207 offset:21504
	ds_read_b128 v[208:211], v207 offset:22528
	ds_read_b128 v[212:215], v207 offset:23552
	global_load_lds_dwordx4 v[190:191], off
	s_add_i32 m0, s47, 0x2000
	s_add_u32 s50, s42, 0x80000
	v_lshl_add_u64 v[216:217], s[42:43], 0, v[166:167]
	s_addc_u32 s51, s43, 0
	s_add_i32 s47, vcc_hi, s59
	global_load_lds_dwordx4 v[216:217], off
	v_lshl_add_u64 v[218:219], s[50:51], 0, v[96:97]
	s_mov_b32 m0, s47
	v_lshl_add_u64 v[220:221], s[44:45], 0, v[164:165]
	global_load_lds_dwordx4 v[218:219], off
	s_add_i32 m0, s47, 0x2000
	v_lshl_add_u64 v[218:219], s[50:51], 0, v[166:167]
	global_load_lds_dwordx4 v[218:219], off
	s_mov_b32 m0, s88
	v_lshl_add_u64 v[218:219], s[44:45], 0, v[162:163]
	global_load_lds_dwordx4 v[218:219], off
	s_mov_b32 m0, s28
	s_nop 0
	global_load_lds_dwordx4 v[220:221], off
	s_waitcnt vmcnt(8) lgkmcnt(0)
	s_barrier
	s_setprio 1
	v_mfma_f32_16x16x32_bf16 v[28:31], v[80:83], v[174:177], v[28:31]
	v_mfma_f32_16x16x32_bf16 v[20:23], v[106:109], v[174:177], v[20:23]
	v_mfma_f32_16x16x32_bf16 v[60:63], v[80:83], v[182:185], v[60:63]
	v_mfma_f32_16x16x32_bf16 v[56:59], v[106:109], v[182:185], v[56:59]
	v_mfma_f32_16x16x32_bf16 v[48:51], v[80:83], v[196:199], v[48:51]
	v_mfma_f32_16x16x32_bf16 v[40:43], v[106:109], v[196:199], v[40:43]
	v_mfma_f32_16x16x32_bf16 v[12:15], v[80:83], v[208:211], v[12:15]
	v_mfma_f32_16x16x32_bf16 v[4:7], v[106:109], v[208:211], v[4:7]
	v_mfma_f32_16x16x32_bf16 v[28:31], v[102:105], v[178:181], v[28:31]
	v_mfma_f32_16x16x32_bf16 v[20:23], v[110:113], v[178:181], v[20:23]
	v_mfma_f32_16x16x32_bf16 v[60:63], v[102:105], v[186:189], v[60:63]
	v_mfma_f32_16x16x32_bf16 v[56:59], v[110:113], v[186:189], v[56:59]
	v_mfma_f32_16x16x32_bf16 v[48:51], v[102:105], v[200:203], v[48:51]
	v_mfma_f32_16x16x32_bf16 v[40:43], v[110:113], v[200:203], v[40:43]
	v_mfma_f32_16x16x32_bf16 v[12:15], v[102:105], v[212:215], v[12:15]
	v_mfma_f32_16x16x32_bf16 v[4:7], v[110:113], v[212:215], v[4:7]
	v_mfma_f32_16x16x32_bf16 v[24:27], v[114:117], v[174:177], v[24:27]
	v_mfma_f32_16x16x32_bf16 v[16:19], v[122:125], v[174:177], v[16:19]
	v_mfma_f32_16x16x32_bf16 v[52:55], v[114:117], v[182:185], v[52:55]
	v_mfma_f32_16x16x32_bf16 v[44:47], v[122:125], v[182:185], v[44:47]
	v_mfma_f32_16x16x32_bf16 v[36:39], v[114:117], v[196:199], v[36:39]
	v_mfma_f32_16x16x32_bf16 v[32:35], v[122:125], v[196:199], v[32:35]
	v_mfma_f32_16x16x32_bf16 v[8:11], v[114:117], v[208:211], v[8:11]
	v_mfma_f32_16x16x32_bf16 v[0:3], v[122:125], v[208:211], v[0:3]
	v_mfma_f32_16x16x32_bf16 v[24:27], v[118:121], v[178:181], v[24:27]
	v_mfma_f32_16x16x32_bf16 v[16:19], v[126:129], v[178:181], v[16:19]
	v_mfma_f32_16x16x32_bf16 v[52:55], v[118:121], v[186:189], v[52:55]
	v_mfma_f32_16x16x32_bf16 v[44:47], v[126:129], v[186:189], v[44:47]
	v_mfma_f32_16x16x32_bf16 v[36:39], v[118:121], v[200:203], v[36:39]
	v_mfma_f32_16x16x32_bf16 v[32:35], v[126:129], v[200:203], v[32:35]
	v_mfma_f32_16x16x32_bf16 v[8:11], v[118:121], v[212:215], v[8:11]
	v_mfma_f32_16x16x32_bf16 v[0:3], v[126:129], v[212:215], v[0:3]
	s_setprio 0
	s_barrier
	s_add_i32 s47, 0, 0x18000
	s_add_i32 s50, 0, 0x1c000
	v_add_u32_e32 v110, s47, v204
	v_add_u32_e32 v126, s50, v204
	ds_read_b128 v[80:83], v110
	ds_read_b128 v[102:105], v110 offset:1024
	ds_read_b128 v[106:109], v110 offset:2048
	ds_read_b128 v[110:113], v110 offset:3072
	ds_read_b128 v[114:117], v126
	ds_read_b128 v[118:121], v126 offset:1024
	ds_read_b128 v[122:125], v126 offset:2048
	ds_read_b128 v[126:129], v126 offset:3072
	s_add_u32 s44, s44, 0x80000
	s_addc_u32 s45, s45, 0
	s_mov_b32 m0, s29
	v_lshl_add_u64 v[222:223], s[44:45], 0, v[162:163]
	ds_read_b128 v[174:177], v207 offset:32768
	ds_read_b128 v[178:181], v207 offset:33792
	ds_read_b128 v[182:185], v207 offset:34816
	ds_read_b128 v[186:189], v207 offset:35840
	ds_read_b128 v[196:199], v207 offset:36864
	ds_read_b128 v[200:203], v207 offset:37888
	ds_read_b128 v[208:211], v207 offset:38912
	ds_read_b128 v[212:215], v207 offset:39936
	global_load_lds_dwordx4 v[222:223], off
	s_mov_b32 m0, s30
	v_lshl_add_u64 v[222:223], s[44:45], 0, v[164:165]
	global_load_lds_dwordx4 v[222:223], off
	s_waitcnt vmcnt(8) lgkmcnt(0)
	s_barrier
	s_setprio 1
	v_mfma_f32_16x16x32_bf16 v[98:101], v[80:83], v[174:177], v[98:101]
	v_mfma_f32_16x16x32_bf16 v[88:91], v[106:109], v[174:177], v[88:91]
	v_mfma_f32_16x16x32_bf16 v[158:161], v[80:83], v[182:185], v[158:161]
	v_mfma_f32_16x16x32_bf16 v[154:157], v[106:109], v[182:185], v[154:157]
	v_mfma_f32_16x16x32_bf16 v[146:149], v[80:83], v[196:199], v[146:149]
	v_mfma_f32_16x16x32_bf16 v[138:141], v[106:109], v[196:199], v[138:141]
	v_mfma_f32_16x16x32_bf16 v[76:79], v[80:83], v[208:211], v[76:79]
	v_mfma_f32_16x16x32_bf16 v[68:71], v[106:109], v[208:211], v[68:71]
	v_mfma_f32_16x16x32_bf16 v[98:101], v[102:105], v[178:181], v[98:101]
	v_mfma_f32_16x16x32_bf16 v[88:91], v[110:113], v[178:181], v[88:91]
	v_mfma_f32_16x16x32_bf16 v[158:161], v[102:105], v[186:189], v[158:161]
	v_mfma_f32_16x16x32_bf16 v[154:157], v[110:113], v[186:189], v[154:157]
	v_mfma_f32_16x16x32_bf16 v[146:149], v[102:105], v[200:203], v[146:149]
	v_mfma_f32_16x16x32_bf16 v[138:141], v[110:113], v[200:203], v[138:141]
	v_mfma_f32_16x16x32_bf16 v[76:79], v[102:105], v[212:215], v[76:79]
	v_mfma_f32_16x16x32_bf16 v[68:71], v[110:113], v[212:215], v[68:71]
	v_mfma_f32_16x16x32_bf16 v[92:95], v[114:117], v[174:177], v[92:95]
	v_mfma_f32_16x16x32_bf16 v[84:87], v[122:125], v[174:177], v[84:87]
	v_mfma_f32_16x16x32_bf16 v[150:153], v[114:117], v[182:185], v[150:153]
	v_mfma_f32_16x16x32_bf16 v[142:145], v[122:125], v[182:185], v[142:145]
	v_mfma_f32_16x16x32_bf16 v[134:137], v[114:117], v[196:199], v[134:137]
	v_mfma_f32_16x16x32_bf16 v[130:133], v[122:125], v[196:199], v[130:133]
	v_mfma_f32_16x16x32_bf16 v[72:75], v[114:117], v[208:211], v[72:75]
	v_mfma_f32_16x16x32_bf16 v[64:67], v[122:125], v[208:211], v[64:67]
	v_mfma_f32_16x16x32_bf16 v[92:95], v[118:121], v[178:181], v[92:95]
	v_mfma_f32_16x16x32_bf16 v[84:87], v[126:129], v[178:181], v[84:87]
	v_mfma_f32_16x16x32_bf16 v[150:153], v[118:121], v[186:189], v[150:153]
	v_mfma_f32_16x16x32_bf16 v[142:145], v[126:129], v[186:189], v[142:145]
	v_mfma_f32_16x16x32_bf16 v[134:137], v[118:121], v[200:203], v[134:137]
	v_mfma_f32_16x16x32_bf16 v[130:133], v[126:129], v[200:203], v[130:133]
	v_mfma_f32_16x16x32_bf16 v[72:75], v[118:121], v[212:215], v[72:75]
	v_mfma_f32_16x16x32_bf16 v[64:67], v[126:129], v[212:215], v[64:67]
	s_setprio 0
	s_barrier
	s_add_i32 s44, s47, s59
	v_lshl_add_u64 v[190:191], v[190:191], 0, s[82:83]
	s_mov_b32 m0, s44
	ds_read_b128 v[174:177], v207 offset:49152
	ds_read_b128 v[178:181], v207 offset:50176
	ds_read_b128 v[182:185], v207 offset:51200
	ds_read_b128 v[186:189], v207 offset:52224
	ds_read_b128 v[196:199], v207 offset:53248
	ds_read_b128 v[200:203], v207 offset:54272
	ds_read_b128 v[208:211], v207 offset:55296
	ds_read_b128 v[212:215], v207 offset:56320
	global_load_lds_dwordx4 v[190:191], off
	s_add_i32 m0, s44, 0x2000
	s_add_u32 s42, s42, 0x80080
	v_lshl_add_u64 v[190:191], v[216:217], 0, s[82:83]
	s_addc_u32 s43, s43, 0
	s_add_i32 s44, s50, s59
	global_load_lds_dwordx4 v[190:191], off
	s_mov_b32 m0, s44
	v_lshl_add_u64 v[190:191], s[42:43], 0, v[96:97]
	global_load_lds_dwordx4 v[190:191], off
	s_add_i32 m0, s44, 0x2000
	v_lshl_add_u64 v[190:191], s[42:43], 0, v[166:167]
	global_load_lds_dwordx4 v[190:191], off
	s_mov_b32 m0, s1
	v_lshl_add_u64 v[190:191], v[218:219], 0, s[82:83]
	global_load_lds_dwordx4 v[190:191], off
	s_mov_b32 m0, s0
	v_lshl_add_u64 v[190:191], v[220:221], 0, s[82:83]
	global_load_lds_dwordx4 v[190:191], off
	s_waitcnt vmcnt(8) lgkmcnt(0)
	s_barrier
	s_setprio 1
	v_mfma_f32_16x16x32_bf16 v[28:31], v[80:83], v[174:177], v[28:31]
	v_mfma_f32_16x16x32_bf16 v[20:23], v[106:109], v[174:177], v[20:23]
	v_mfma_f32_16x16x32_bf16 v[60:63], v[80:83], v[182:185], v[60:63]
	v_mfma_f32_16x16x32_bf16 v[56:59], v[106:109], v[182:185], v[56:59]
	v_mfma_f32_16x16x32_bf16 v[48:51], v[80:83], v[196:199], v[48:51]
	v_mfma_f32_16x16x32_bf16 v[40:43], v[106:109], v[196:199], v[40:43]
	v_mfma_f32_16x16x32_bf16 v[12:15], v[80:83], v[208:211], v[12:15]
	v_mfma_f32_16x16x32_bf16 v[4:7], v[106:109], v[208:211], v[4:7]
	v_mfma_f32_16x16x32_bf16 v[28:31], v[102:105], v[178:181], v[28:31]
	v_mfma_f32_16x16x32_bf16 v[20:23], v[110:113], v[178:181], v[20:23]
	v_mfma_f32_16x16x32_bf16 v[60:63], v[102:105], v[186:189], v[60:63]
	v_mfma_f32_16x16x32_bf16 v[56:59], v[110:113], v[186:189], v[56:59]
	v_mfma_f32_16x16x32_bf16 v[48:51], v[102:105], v[200:203], v[48:51]
	v_mfma_f32_16x16x32_bf16 v[40:43], v[110:113], v[200:203], v[40:43]
	v_mfma_f32_16x16x32_bf16 v[12:15], v[102:105], v[212:215], v[12:15]
	v_mfma_f32_16x16x32_bf16 v[4:7], v[110:113], v[212:215], v[4:7]
	v_mfma_f32_16x16x32_bf16 v[24:27], v[114:117], v[174:177], v[24:27]
	v_mfma_f32_16x16x32_bf16 v[16:19], v[122:125], v[174:177], v[16:19]
	v_mfma_f32_16x16x32_bf16 v[52:55], v[114:117], v[182:185], v[52:55]
	v_mfma_f32_16x16x32_bf16 v[44:47], v[122:125], v[182:185], v[44:47]
	v_mfma_f32_16x16x32_bf16 v[36:39], v[114:117], v[196:199], v[36:39]
	v_mfma_f32_16x16x32_bf16 v[32:35], v[122:125], v[196:199], v[32:35]
	v_mfma_f32_16x16x32_bf16 v[8:11], v[114:117], v[208:211], v[8:11]
	v_mfma_f32_16x16x32_bf16 v[0:3], v[122:125], v[208:211], v[0:3]
	v_mfma_f32_16x16x32_bf16 v[24:27], v[118:121], v[178:181], v[24:27]
	v_mfma_f32_16x16x32_bf16 v[16:19], v[126:129], v[178:181], v[16:19]
	v_mfma_f32_16x16x32_bf16 v[52:55], v[118:121], v[186:189], v[52:55]
	v_mfma_f32_16x16x32_bf16 v[44:47], v[126:129], v[186:189], v[44:47]
	v_mfma_f32_16x16x32_bf16 v[36:39], v[118:121], v[200:203], v[36:39]
	v_mfma_f32_16x16x32_bf16 v[32:35], v[126:129], v[200:203], v[32:35]
	v_mfma_f32_16x16x32_bf16 v[8:11], v[118:121], v[212:215], v[8:11]
	v_mfma_f32_16x16x32_bf16 v[0:3], v[126:129], v[212:215], v[0:3]
	s_setprio 0
	s_barrier
	s_add_u32 s40, s40, 0x100
	s_addc_u32 s41, s41, 0
	s_add_u32 s92, s92, 0x100
	s_addc_u32 vcc_lo, vcc_lo, 0
	s_cmp_ge_i32 s46, s49
	s_mov_b32 s44, s46
	s_cbranch_scc0 .LBB0_1145
	s_and_b64 vcc, exec, s[56:57]
	s_cbranch_vccz .LBB0_1148
	s_barrier

.LBB0_1349:
	s_add_i32 s46, s20, 2
	s_add_u32 s18, s16, 0x100
	s_addc_u32 s19, s17, 0
	s_add_i32 s47, 0, 0x10000
	s_cmp_eq_u32 s56, s20
	s_cselect_b32 s23, s13, s19
	s_cselect_b32 s22, s12, s18
	v_add_u32_e32 v142, s47, v145
	s_cselect_b32 s21, s15, s58
	s_cselect_b32 s20, s14, s57
	s_add_i32 s50, 0, 0x14000
	ds_read_b128 v[148:151], v142
	ds_read_b128 v[152:155], v142 offset:1024
	ds_read_b128 v[156:159], v142 offset:2048
	ds_read_b128 v[160:163], v142 offset:3072
	v_add_u32_e32 v142, s50, v145
	ds_read_b128 v[164:167], v142
	ds_read_b128 v[168:171], v142 offset:1024
	ds_read_b128 v[172:175], v142 offset:2048
	ds_read_b128 v[176:179], v142 offset:3072
	v_lshl_add_u64 v[142:143], s[16:17], 0, v[138:139]
	s_add_i32 m0, s36, 0xc000
	ds_read_b128 v[180:183], v146
	ds_read_b128 v[184:187], v146 offset:1024
	ds_read_b128 v[188:191], v146 offset:2048
	ds_read_b128 v[196:199], v146 offset:3072
	ds_read_b128 v[200:203], v146 offset:4096
	ds_read_b128 v[204:207], v146 offset:5120
	ds_read_b128 v[208:211], v146 offset:6144
	ds_read_b128 v[212:215], v146 offset:7168
	global_load_lds_dwordx4 v[142:143], off
	s_add_i32 m0, s36, 0xe000
	v_lshl_add_u64 v[142:143], s[16:17], 0, v[140:141]
	global_load_lds_dwordx4 v[142:143], off
	s_waitcnt vmcnt(8) lgkmcnt(0)
	s_barrier
	s_setprio 1
	v_mfma_f32_16x16x32_bf16 v[126:129], v[148:151], v[180:183], v[126:129]
	v_mfma_f32_16x16x32_bf16 v[122:125], v[156:159], v[180:183], v[122:125]
	v_mfma_f32_16x16x32_bf16 v[118:121], v[148:151], v[188:191], v[118:121]
	v_mfma_f32_16x16x32_bf16 v[110:113], v[156:159], v[188:191], v[110:113]
	v_mfma_f32_16x16x32_bf16 v[102:105], v[148:151], v[200:203], v[102:105]
	v_mfma_f32_16x16x32_bf16 v[92:95], v[156:159], v[200:203], v[92:95]
	v_mfma_f32_16x16x32_bf16 v[84:87], v[148:151], v[208:211], v[84:87]
	v_mfma_f32_16x16x32_bf16 v[76:79], v[156:159], v[208:211], v[76:79]
	v_mfma_f32_16x16x32_bf16 v[126:129], v[152:155], v[184:187], v[126:129]
	v_mfma_f32_16x16x32_bf16 v[122:125], v[160:163], v[184:187], v[122:125]
	v_mfma_f32_16x16x32_bf16 v[118:121], v[152:155], v[196:199], v[118:121]
	v_mfma_f32_16x16x32_bf16 v[110:113], v[160:163], v[196:199], v[110:113]
	v_mfma_f32_16x16x32_bf16 v[102:105], v[152:155], v[204:207], v[102:105]
	v_mfma_f32_16x16x32_bf16 v[92:95], v[160:163], v[204:207], v[92:95]
	v_mfma_f32_16x16x32_bf16 v[84:87], v[152:155], v[212:215], v[84:87]
	v_mfma_f32_16x16x32_bf16 v[76:79], v[160:163], v[212:215], v[76:79]
	v_mfma_f32_16x16x32_bf16 v[114:117], v[164:167], v[180:183], v[114:117]
	v_mfma_f32_16x16x32_bf16 v[106:109], v[172:175], v[180:183], v[106:109]
	v_mfma_f32_16x16x32_bf16 v[98:101], v[164:167], v[188:191], v[98:101]
	v_mfma_f32_16x16x32_bf16 v[88:91], v[172:175], v[188:191], v[88:91]
	v_mfma_f32_16x16x32_bf16 v[80:83], v[164:167], v[200:203], v[80:83]
	v_mfma_f32_16x16x32_bf16 v[72:75], v[172:175], v[200:203], v[72:75]
	v_mfma_f32_16x16x32_bf16 v[68:71], v[164:167], v[208:211], v[68:71]
	v_mfma_f32_16x16x32_bf16 v[64:67], v[172:175], v[208:211], v[64:67]
	v_mfma_f32_16x16x32_bf16 v[114:117], v[168:171], v[184:187], v[114:117]
	v_mfma_f32_16x16x32_bf16 v[106:109], v[176:179], v[184:187], v[106:109]
	v_mfma_f32_16x16x32_bf16 v[98:101], v[168:171], v[196:199], v[98:101]
	v_mfma_f32_16x16x32_bf16 v[88:91], v[176:179], v[196:199], v[88:91]
	v_mfma_f32_16x16x32_bf16 v[80:83], v[168:171], v[204:207], v[80:83]
	v_mfma_f32_16x16x32_bf16 v[72:75], v[176:179], v[204:207], v[72:75]
	v_mfma_f32_16x16x32_bf16 v[68:71], v[168:171], v[212:215], v[68:71]
	v_mfma_f32_16x16x32_bf16 v[64:67], v[176:179], v[212:215], v[64:67]
	s_setprio 0
	s_barrier
	s_add_i32 s16, s47, s31
	v_lshl_add_u64 v[142:143], s[20:21], 0, v[132:133]
	s_mov_b32 m0, s16
	ds_read_b128 v[180:183], v146 offset:16384
	ds_read_b128 v[184:187], v146 offset:17408
	ds_read_b128 v[188:191], v146 offset:18432
	ds_read_b128 v[196:199], v146 offset:19456
	ds_read_b128 v[200:203], v146 offset:20480
	ds_read_b128 v[204:207], v146 offset:21504
	ds_read_b128 v[208:211], v146 offset:22528
	ds_read_b128 v[212:215], v146 offset:23552
	global_load_lds_dwordx4 v[142:143], off
	s_add_i32 m0, s16, 0x2000
	s_add_u32 s16, s20, 0x160000
	v_lshl_add_u64 v[192:193], s[20:21], 0, v[136:137]
	s_addc_u32 s17, s21, 0
	s_add_i32 s47, s50, s31
	global_load_lds_dwordx4 v[192:193], off
	v_lshl_add_u64 v[216:217], s[16:17], 0, v[132:133]
	s_mov_b32 m0, s47
	v_lshl_add_u64 v[218:219], s[22:23], 0, v[134:135]
	global_load_lds_dwordx4 v[216:217], off
	s_add_i32 m0, s47, 0x2000
	v_lshl_add_u64 v[216:217], s[16:17], 0, v[136:137]
	global_load_lds_dwordx4 v[216:217], off
	s_mov_b32 m0, s36
	v_lshl_add_u64 v[216:217], s[22:23], 0, v[130:131]
	global_load_lds_dwordx4 v[216:217], off
	s_mov_b32 m0, s37
	s_nop 0
	global_load_lds_dwordx4 v[218:219], off
	s_waitcnt vmcnt(8) lgkmcnt(0)
	s_barrier
	s_setprio 1
	v_mfma_f32_16x16x32_bf16 v[60:63], v[148:151], v[180:183], v[60:63]
	v_mfma_f32_16x16x32_bf16 v[56:59], v[156:159], v[180:183], v[56:59]
	v_mfma_f32_16x16x32_bf16 v[52:55], v[148:151], v[188:191], v[52:55]
	v_mfma_f32_16x16x32_bf16 v[44:47], v[156:159], v[188:191], v[44:47]
	v_mfma_f32_16x16x32_bf16 v[36:39], v[148:151], v[200:203], v[36:39]
	v_mfma_f32_16x16x32_bf16 v[28:31], v[156:159], v[200:203], v[28:31]
	v_mfma_f32_16x16x32_bf16 v[20:23], v[148:151], v[208:211], v[20:23]
	v_mfma_f32_16x16x32_bf16 v[12:15], v[156:159], v[208:211], v[12:15]
	v_mfma_f32_16x16x32_bf16 v[60:63], v[152:155], v[184:187], v[60:63]
	v_mfma_f32_16x16x32_bf16 v[56:59], v[160:163], v[184:187], v[56:59]
	v_mfma_f32_16x16x32_bf16 v[52:55], v[152:155], v[196:199], v[52:55]
	v_mfma_f32_16x16x32_bf16 v[44:47], v[160:163], v[196:199], v[44:47]
	v_mfma_f32_16x16x32_bf16 v[36:39], v[152:155], v[204:207], v[36:39]
	v_mfma_f32_16x16x32_bf16 v[28:31], v[160:163], v[204:207], v[28:31]
	v_mfma_f32_16x16x32_bf16 v[20:23], v[152:155], v[212:215], v[20:23]
	v_mfma_f32_16x16x32_bf16 v[12:15], v[160:163], v[212:215], v[12:15]
	v_mfma_f32_16x16x32_bf16 v[48:51], v[164:167], v[180:183], v[48:51]
	v_mfma_f32_16x16x32_bf16 v[40:43], v[172:175], v[180:183], v[40:43]
	v_mfma_f32_16x16x32_bf16 v[32:35], v[164:167], v[188:191], v[32:35]
	v_mfma_f32_16x16x32_bf16 v[24:27], v[172:175], v[188:191], v[24:27]
	v_mfma_f32_16x16x32_bf16 v[16:19], v[164:167], v[200:203], v[16:19]
	v_mfma_f32_16x16x32_bf16 v[8:11], v[172:175], v[200:203], v[8:11]
	v_mfma_f32_16x16x32_bf16 v[4:7], v[164:167], v[208:211], v[4:7]
	v_mfma_f32_16x16x32_bf16 v[0:3], v[172:175], v[208:211], v[0:3]
	v_mfma_f32_16x16x32_bf16 v[48:51], v[168:171], v[184:187], v[48:51]
	v_mfma_f32_16x16x32_bf16 v[40:43], v[176:179], v[184:187], v[40:43]
	v_mfma_f32_16x16x32_bf16 v[32:35], v[168:171], v[196:199], v[32:35]
	v_mfma_f32_16x16x32_bf16 v[24:27], v[176:179], v[196:199], v[24:27]
	v_mfma_f32_16x16x32_bf16 v[16:19], v[168:171], v[204:207], v[16:19]
	v_mfma_f32_16x16x32_bf16 v[8:11], v[176:179], v[204:207], v[8:11]
	v_mfma_f32_16x16x32_bf16 v[4:7], v[168:171], v[212:215], v[4:7]
	v_mfma_f32_16x16x32_bf16 v[0:3], v[176:179], v[212:215], v[0:3]
	s_setprio 0
	s_barrier
	s_add_i32 s47, 0, 0x18000
	v_add_u32_e32 v147, s47, v145
	s_add_i32 s50, 0, 0x1c000
	ds_read_b128 v[148:151], v147
	ds_read_b128 v[152:155], v147 offset:1024
	ds_read_b128 v[156:159], v147 offset:2048
	ds_read_b128 v[160:163], v147 offset:3072
	v_add_u32_e32 v147, s50, v145
	ds_read_b128 v[164:167], v147
	ds_read_b128 v[168:171], v147 offset:1024
	ds_read_b128 v[172:175], v147 offset:2048
	ds_read_b128 v[176:179], v147 offset:3072
	s_add_u32 s16, s22, 0x160000
	s_addc_u32 s17, s23, 0
	s_mov_b32 m0, s38
	v_lshl_add_u64 v[220:221], s[16:17], 0, v[130:131]
	ds_read_b128 v[180:183], v146 offset:32768
	ds_read_b128 v[184:187], v146 offset:33792
	ds_read_b128 v[188:191], v146 offset:34816
	ds_read_b128 v[196:199], v146 offset:35840
	ds_read_b128 v[200:203], v146 offset:36864
	ds_read_b128 v[204:207], v146 offset:37888
	ds_read_b128 v[208:211], v146 offset:38912
	ds_read_b128 v[212:215], v146 offset:39936
	global_load_lds_dwordx4 v[220:221], off
	s_mov_b32 m0, s39
	v_lshl_add_u64 v[220:221], s[16:17], 0, v[134:135]
	global_load_lds_dwordx4 v[220:221], off
	s_waitcnt vmcnt(8) lgkmcnt(0)
	s_barrier
	s_setprio 1
	v_mfma_f32_16x16x32_bf16 v[126:129], v[148:151], v[180:183], v[126:129]
	v_mfma_f32_16x16x32_bf16 v[122:125], v[156:159], v[180:183], v[122:125]
	v_mfma_f32_16x16x32_bf16 v[118:121], v[148:151], v[188:191], v[118:121]
	v_mfma_f32_16x16x32_bf16 v[110:113], v[156:159], v[188:191], v[110:113]
	v_mfma_f32_16x16x32_bf16 v[102:105], v[148:151], v[200:203], v[102:105]
	v_mfma_f32_16x16x32_bf16 v[92:95], v[156:159], v[200:203], v[92:95]
	v_mfma_f32_16x16x32_bf16 v[84:87], v[148:151], v[208:211], v[84:87]
	v_mfma_f32_16x16x32_bf16 v[76:79], v[156:159], v[208:211], v[76:79]
	v_mfma_f32_16x16x32_bf16 v[126:129], v[152:155], v[184:187], v[126:129]
	v_mfma_f32_16x16x32_bf16 v[122:125], v[160:163], v[184:187], v[122:125]
	v_mfma_f32_16x16x32_bf16 v[118:121], v[152:155], v[196:199], v[118:121]
	v_mfma_f32_16x16x32_bf16 v[110:113], v[160:163], v[196:199], v[110:113]
	v_mfma_f32_16x16x32_bf16 v[102:105], v[152:155], v[204:207], v[102:105]
	v_mfma_f32_16x16x32_bf16 v[92:95], v[160:163], v[204:207], v[92:95]
	v_mfma_f32_16x16x32_bf16 v[84:87], v[152:155], v[212:215], v[84:87]
	v_mfma_f32_16x16x32_bf16 v[76:79], v[160:163], v[212:215], v[76:79]
	v_mfma_f32_16x16x32_bf16 v[114:117], v[164:167], v[180:183], v[114:117]
	v_mfma_f32_16x16x32_bf16 v[106:109], v[172:175], v[180:183], v[106:109]
	v_mfma_f32_16x16x32_bf16 v[98:101], v[164:167], v[188:191], v[98:101]
	v_mfma_f32_16x16x32_bf16 v[88:91], v[172:175], v[188:191], v[88:91]
	v_mfma_f32_16x16x32_bf16 v[80:83], v[164:167], v[200:203], v[80:83]
	v_mfma_f32_16x16x32_bf16 v[72:75], v[172:175], v[200:203], v[72:75]
	v_mfma_f32_16x16x32_bf16 v[68:71], v[164:167], v[208:211], v[68:71]
	v_mfma_f32_16x16x32_bf16 v[64:67], v[172:175], v[208:211], v[64:67]
	v_mfma_f32_16x16x32_bf16 v[114:117], v[168:171], v[184:187], v[114:117]
	v_mfma_f32_16x16x32_bf16 v[106:109], v[176:179], v[184:187], v[106:109]
	v_mfma_f32_16x16x32_bf16 v[98:101], v[168:171], v[196:199], v[98:101]
	v_mfma_f32_16x16x32_bf16 v[88:91], v[176:179], v[196:199], v[88:91]
	v_mfma_f32_16x16x32_bf16 v[80:83], v[168:171], v[204:207], v[80:83]
	v_mfma_f32_16x16x32_bf16 v[72:75], v[176:179], v[204:207], v[72:75]
	v_mfma_f32_16x16x32_bf16 v[68:71], v[168:171], v[212:215], v[68:71]
	v_mfma_f32_16x16x32_bf16 v[64:67], v[176:179], v[212:215], v[64:67]
	s_setprio 0
	s_barrier
	s_add_i32 s16, s47, s31
	v_lshl_add_u64 v[142:143], v[142:143], 0, s[82:83]
	s_mov_b32 m0, s16
	ds_read_b128 v[180:183], v146 offset:49152
	ds_read_b128 v[184:187], v146 offset:50176
	ds_read_b128 v[188:191], v146 offset:51200
	ds_read_b128 v[196:199], v146 offset:52224
	ds_read_b128 v[200:203], v146 offset:53248
	ds_read_b128 v[204:207], v146 offset:54272
	ds_read_b128 v[208:211], v146 offset:55296
	ds_read_b128 v[212:215], v146 offset:56320
	global_load_lds_dwordx4 v[142:143], off
	s_add_i32 m0, s16, 0x2000
	s_add_u32 s16, s20, 0x160080
	v_lshl_add_u64 v[142:143], v[192:193], 0, s[82:83]
	s_addc_u32 s17, s21, 0
	s_add_i32 s20, s50, s31
	global_load_lds_dwordx4 v[142:143], off
	s_mov_b32 m0, s20
	v_lshl_add_u64 v[142:143], s[16:17], 0, v[132:133]
	global_load_lds_dwordx4 v[142:143], off
	s_add_i32 m0, s20, 0x2000
	v_lshl_add_u64 v[142:143], s[16:17], 0, v[136:137]
	global_load_lds_dwordx4 v[142:143], off
	s_mov_b32 m0, s40
	v_lshl_add_u64 v[142:143], v[216:217], 0, s[82:83]
	global_load_lds_dwordx4 v[142:143], off
	s_mov_b32 m0, s41
	v_lshl_add_u64 v[142:143], v[218:219], 0, s[82:83]
	global_load_lds_dwordx4 v[142:143], off
	s_waitcnt vmcnt(8) lgkmcnt(0)
	s_barrier
	s_setprio 1
	v_mfma_f32_16x16x32_bf16 v[60:63], v[148:151], v[180:183], v[60:63]
	v_mfma_f32_16x16x32_bf16 v[56:59], v[156:159], v[180:183], v[56:59]
	v_mfma_f32_16x16x32_bf16 v[52:55], v[148:151], v[188:191], v[52:55]
	v_mfma_f32_16x16x32_bf16 v[44:47], v[156:159], v[188:191], v[44:47]
	v_mfma_f32_16x16x32_bf16 v[36:39], v[148:151], v[200:203], v[36:39]
	v_mfma_f32_16x16x32_bf16 v[28:31], v[156:159], v[200:203], v[28:31]
	v_mfma_f32_16x16x32_bf16 v[20:23], v[148:151], v[208:211], v[20:23]
	v_mfma_f32_16x16x32_bf16 v[12:15], v[156:159], v[208:211], v[12:15]
	v_mfma_f32_16x16x32_bf16 v[60:63], v[152:155], v[184:187], v[60:63]
	v_mfma_f32_16x16x32_bf16 v[56:59], v[160:163], v[184:187], v[56:59]
	v_mfma_f32_16x16x32_bf16 v[52:55], v[152:155], v[196:199], v[52:55]
	v_mfma_f32_16x16x32_bf16 v[44:47], v[160:163], v[196:199], v[44:47]
	v_mfma_f32_16x16x32_bf16 v[36:39], v[152:155], v[204:207], v[36:39]
	v_mfma_f32_16x16x32_bf16 v[28:31], v[160:163], v[204:207], v[28:31]
	v_mfma_f32_16x16x32_bf16 v[20:23], v[152:155], v[212:215], v[20:23]
	v_mfma_f32_16x16x32_bf16 v[12:15], v[160:163], v[212:215], v[12:15]
	v_mfma_f32_16x16x32_bf16 v[48:51], v[164:167], v[180:183], v[48:51]
	v_mfma_f32_16x16x32_bf16 v[40:43], v[172:175], v[180:183], v[40:43]
	v_mfma_f32_16x16x32_bf16 v[32:35], v[164:167], v[188:191], v[32:35]
	v_mfma_f32_16x16x32_bf16 v[24:27], v[172:175], v[188:191], v[24:27]
	v_mfma_f32_16x16x32_bf16 v[16:19], v[164:167], v[200:203], v[16:19]
	v_mfma_f32_16x16x32_bf16 v[8:11], v[172:175], v[200:203], v[8:11]
	v_mfma_f32_16x16x32_bf16 v[4:7], v[164:167], v[208:211], v[4:7]
	v_mfma_f32_16x16x32_bf16 v[0:3], v[172:175], v[208:211], v[0:3]
	v_mfma_f32_16x16x32_bf16 v[48:51], v[168:171], v[184:187], v[48:51]
	v_mfma_f32_16x16x32_bf16 v[40:43], v[176:179], v[184:187], v[40:43]
	v_mfma_f32_16x16x32_bf16 v[32:35], v[168:171], v[196:199], v[32:35]
	v_mfma_f32_16x16x32_bf16 v[24:27], v[176:179], v[196:199], v[24:27]
	v_mfma_f32_16x16x32_bf16 v[16:19], v[168:171], v[204:207], v[16:19]
	v_mfma_f32_16x16x32_bf16 v[8:11], v[176:179], v[204:207], v[8:11]
	v_mfma_f32_16x16x32_bf16 v[4:7], v[168:171], v[212:215], v[4:7]
	v_mfma_f32_16x16x32_bf16 v[0:3], v[176:179], v[212:215], v[0:3]
	s_setprio 0
	s_barrier
	s_add_u32 s57, s57, 0x100
	s_addc_u32 s58, s58, 0
	s_cmp_ge_i32 s46, s55
	s_mov_b64 s[16:17], s[18:19]
	s_mov_b32 s20, s46
	s_cbranch_scc0 .LBB0_1349
	s_and_b64 vcc, exec, s[10:11]
	s_cbranch_vccz .LBB0_1352
	s_barrier
